# FFN up-projection epilogue: removed 192 dead zero-initialisations of row_ror DPP destinations (hazard distances re-checked)
# baseline (speedup 1.0000x reference)
;     __device__ __forceinline__ void operator()(const f32x4 (&acc_c)[2][2][4][2], const Unit& u, int wr, int wc, int fr, int fq) const {
;     ...
;         for (int ai = 0; ai < 2; ++ai)
; #pragma unroll
;             for (int m = 0; m < 4; ++m) { const float rs = rsqrtf(rsv[ai][m] * (1.0f / 1024.0f) + EPS);
; #pragma unroll
;                 for (int bj = 0; bj < 2; ++bj)
; #pragma unroll
;                     for (int n = 0; n < 2; ++n) acc[ai][bj][m][n] *= rs; }
;         if (fr >= 14) {
; #pragma unroll
;             for (int ai = 0; ai < 2; ++ai)
; #pragma unroll
;                 for (int bj = 0; bj < 2; ++bj)
; #pragma unroll
;                     for (int n = 0; n < 2; ++n) *(LAS f32x4*)(xch + ((ai * 2 + wr) * 4 + wc) * 128 + (fr - 14) * 64 + bj * 32 + 8 * fq + 4 * n) = acc[ai][bj][3][n];
;         }
;         if ((wr == 1 && fr >= 14) || (wr == 0 && fr < 2)) {
;             const int ai = wr, m = wr ? 3 : 0, srow = wr ? (2 + fr - 14) : fr;
; #pragma unroll
;             for (int bj = 0; bj < 2; ++bj) { const f32x4 a = wr ? acc[1][bj][3][0] : acc[0][bj][0][0], b = wr ? acc[1][bj][3][1] : acc[0][bj][0][1];
;                 *(u32x4*)(sb + ((size_t)u.pm * 4 + srow) * FF2 + u.pn * 256 + bj * 128 + jl) = pack8(a, b); }
;             (void)ai; (void)m;
;         }
;         asm volatile("s_waitcnt lgkmcnt(0)" ::: "memory");
;         __builtin_amdgcn_s_barrier(); __builtin_amdgcn_s_barrier();
;         asm volatile("" ::: "memory");
; #pragma unroll
;         for (int n = 0; n < 2; ++n) {
;             f32x4 wg[3], wv[3], bg, bv;
; #pragma unroll
;             for (int t = 0; t < 3; ++t) { wg[t] = *(const f32x4*)(cw + t * FF2 + ch0 + 4 * n); wv[t] = *(const f32x4*)(cw + t * FF2 + FF + ch0 + 4 * n); }
;             bg = *(const f32x4*)(cb + ch0 + 4 * n); bv = *(const f32x4*)(cb + FF + ch0 + 4 * n);
; #pragma unroll
;             for (int ai = 0; ai < 2; ++ai) {
;                 f32x4 xpg = {0.f, 0.f, 0.f, 0.f}, xpv = {0.f, 0.f, 0.f, 0.f};
;                 const bool top = (ai == 0 && wr == 0);
;                 if (!top && fr >= 14) { const int ps = (wr == 1) ? ((ai * 2) * 4 + wc) : (((ai - 1) * 2 + 1) * 4 + wc);
;                     xpg = *(const LAS f32x4*)(xch + ps * 128 + (fr - 14) * 64 + 8 * fq + 4 * n); xpv = *(const LAS f32x4*)(xch + ps * 128 + (fr - 14) * 64 + 32 + 8 * fq + 4 * n); }
; #pragma unroll
;                 for (int m = 0; m < 4; ++m) {
.LBB0_1442:
	s_or_b64 exec, exec, s[4:5]
	v_fmamk_f32 v0, v190, 0x3a800000, v216
	v_mul_f32_e32 v190, 0x4b800000, v0
	v_cmp_gt_f32_e32 vcc, s2, v0
	v_fmamk_f32 v147, v147, 0x3a800000, v216
	v_mul_f32_e32 v197, 0x4b800000, v147
	v_cndmask_b32_e32 v0, v0, v190, vcc
	v_rsq_f32_e32 v0, v0
	s_movk_i32 s41, 0x1600
	v_mul_f32_e32 v190, 0x45800000, v0
	v_cndmask_b32_e32 v190, v0, v190, vcc
	v_cmp_gt_f32_e32 vcc, s2, v147
	v_pk_mul_f32 v[210:211], v[126:127], v[190:191] op_sel_hi:[1,0]
	v_pk_mul_f32 v[212:213], v[134:135], v[190:191] op_sel_hi:[1,0]
	v_cndmask_b32_e32 v0, v147, v197, vcc
	v_rsq_f32_e32 v0, v0
	v_pk_mul_f32 v[134:135], v[128:129], v[190:191] op_sel_hi:[1,0]
	v_pk_mul_f32 v[204:205], v[136:137], v[190:191] op_sel_hi:[1,0]
	s_waitcnt lgkmcnt(0)
	v_mov_b32_dpp v242, v148 row_ror:2 row_mask:0xf bank_mask:0xf
	v_mul_f32_e32 v126, 0x45800000, v0
	v_cndmask_b32_e32 v128, v0, v126, vcc
	v_pk_mul_f32 v[126:127], v[132:133], v[128:129] op_sel_hi:[1,0]
	v_pk_mul_f32 v[136:137], v[130:131], v[128:129] op_sel_hi:[1,0]
	v_mov_b32_dpp v132, v152 row_ror:2 row_mask:0xf bank_mask:0xf
	v_mov_b32_dpp v133, v153 row_ror:2 row_mask:0xf bank_mask:0xf
	v_mov_b32_dpp v130, v152 row_ror:1 row_mask:0xf bank_mask:0xf
	v_mov_b32_dpp v132, v206 row_shr:2 row_mask:0xf bank_mask:0xf
	v_mov_b32_dpp v131, v153 row_ror:1 row_mask:0xf bank_mask:0xf
	v_mov_b32_dpp v133, v207 row_shr:2 row_mask:0xf bank_mask:0xf
	v_mov_b32_dpp v130, v206 row_shr:1 row_mask:0xf bank_mask:0xf
	v_mov_b32_dpp v131, v207 row_shr:1 row_mask:0xf bank_mask:0xf
	s_waitcnt vmcnt(7)
	v_pk_mul_f32 v[132:133], v[106:107], v[132:133]
	v_pk_mul_f32 v[124:125], v[124:125], v[128:129] op_sel_hi:[1,0]
	s_waitcnt vmcnt(5)
	v_pk_fma_f32 v[130:131], v[110:111], v[130:131], v[132:133]
	v_pk_mul_f32 v[122:123], v[122:123], v[128:129] op_sel_hi:[1,0]
	s_waitcnt vmcnt(3)
	v_pk_fma_f32 v[130:131], v[206:207], v[114:115], v[130:131]
	s_waitcnt vmcnt(1)
	v_pk_add_f32 v[130:131], v[118:119], v[130:131]
	v_mul_f32_e32 v0, 0xbfb8aa3b, v130
	v_exp_f32_e32 v0, v0
	v_mul_f32_e32 v129, 0xbfb8aa3b, v131
	v_exp_f32_e32 v129, v129
	v_mov_b32_dpp v243, v149 row_ror:2 row_mask:0xf bank_mask:0xf
	v_add_f32_e32 v0, 1.0, v0
	v_rcp_f32_e32 v132, v0
	v_add_f32_e32 v0, 1.0, v129
	v_mov_b32_dpp v152, v148 row_ror:1 row_mask:0xf bank_mask:0xf
	v_mov_b32_dpp v242, v208 row_shr:2 row_mask:0xf bank_mask:0xf
	v_mov_b32_dpp v153, v149 row_ror:1 row_mask:0xf bank_mask:0xf
	v_mov_b32_dpp v243, v209 row_shr:2 row_mask:0xf bank_mask:0xf
	v_rcp_f32_e32 v133, v0
	v_mov_b32_dpp v152, v208 row_shr:1 row_mask:0xf bank_mask:0xf
	v_mov_b32_dpp v153, v209 row_shr:1 row_mask:0xf bank_mask:0xf
	v_pk_mul_f32 v[148:149], v[90:91], v[242:243]
	v_pk_mul_f32 v[130:131], v[130:131], v[132:133]
	v_pk_fma_f32 v[148:149], v[94:95], v[152:153], v[148:149]
	v_pk_fma_f32 v[148:149], v[208:209], v[98:99], v[148:149]
	s_waitcnt vmcnt(0)
	v_pk_add_f32 v[148:149], v[102:103], v[148:149]
	v_mov_b32_dpp v152, v150 row_ror:1 row_mask:0xf bank_mask:0xf
	v_pk_mul_f32 v[130:131], v[148:149], v[130:131]
	v_cvt_pk_f16_f32 v132, v130, v131
	v_mov_b32_dpp v148, v154 row_ror:2 row_mask:0xf bank_mask:0xf
	v_mov_b32_dpp v149, v155 row_ror:2 row_mask:0xf bank_mask:0xf
	v_mov_b32_dpp v130, v154 row_ror:1 row_mask:0xf bank_mask:0xf
	v_mov_b32_dpp v148, v200 row_shr:2 row_mask:0xf bank_mask:0xf
	v_mov_b32_dpp v131, v155 row_ror:1 row_mask:0xf bank_mask:0xf
	v_mov_b32_dpp v149, v201 row_shr:2 row_mask:0xf bank_mask:0xf
	v_mov_b32_dpp v130, v200 row_shr:1 row_mask:0xf bank_mask:0xf
	v_mov_b32_dpp v131, v201 row_shr:1 row_mask:0xf bank_mask:0xf
	v_pk_mul_f32 v[148:149], v[108:109], v[148:149]
	v_pk_fma_f32 v[130:131], v[112:113], v[130:131], v[148:149]
	v_pk_fma_f32 v[130:131], v[200:201], v[116:117], v[130:131]
	v_mov_b32_dpp v154, v150 row_ror:2 row_mask:0xf bank_mask:0xf
	v_pk_add_f32 v[130:131], v[120:121], v[130:131]
	v_mov_b32_dpp v155, v151 row_ror:2 row_mask:0xf bank_mask:0xf
	v_mul_f32_e32 v0, 0xbfb8aa3b, v130
	v_exp_f32_e32 v0, v0
	v_mul_f32_e32 v129, 0xbfb8aa3b, v131
	v_exp_f32_e32 v129, v129
	v_mov_b32_dpp v154, v202 row_shr:2 row_mask:0xf bank_mask:0xf
	v_add_f32_e32 v0, 1.0, v0
	v_rcp_f32_e32 v148, v0
	v_add_f32_e32 v0, 1.0, v129
	v_mov_b32_dpp v153, v151 row_ror:1 row_mask:0xf bank_mask:0xf
	v_mov_b32_dpp v155, v203 row_shr:2 row_mask:0xf bank_mask:0xf
	v_rcp_f32_e32 v149, v0
	v_mov_b32_dpp v152, v202 row_shr:1 row_mask:0xf bank_mask:0xf
	v_mov_b32_dpp v153, v203 row_shr:1 row_mask:0xf bank_mask:0xf
	v_pk_mul_f32 v[150:151], v[92:93], v[154:155]
	v_pk_mul_f32 v[130:131], v[130:131], v[148:149]
	v_pk_fma_f32 v[150:151], v[96:97], v[152:153], v[150:151]
	v_mov_b64_e32 v[148:149], s[12:13]
	v_pk_fma_f32 v[150:151], v[202:203], v[100:101], v[150:151]
	v_pk_add_f32 v[150:151], v[104:105], v[150:151]
	v_pk_mul_f32 v[130:131], v[150:151], v[130:131]
	v_lshlrev_b64 v[150:151], 1, v[214:215]
	v_cvt_pk_f16_f32 v133, v130, v131
	v_mad_i64_i32 v[130:131], s[4:5], v192, s41, v[148:149]
	v_lshl_add_u64 v[130:131], v[130:131], 0, v[150:151]
	global_store_dwordx2 v[130:131], v[132:133], off
	v_mov_b32_dpp v152, v206 row_ror:2 row_mask:0xf bank_mask:0xf
	v_mov_b32_dpp v153, v207 row_ror:2 row_mask:0xf bank_mask:0xf
	v_mov_b32_dpp v132, v206 row_ror:1 row_mask:0xf bank_mask:0xf
	v_mov_b32_dpp v152, v212 row_shr:2 row_mask:0xf bank_mask:0xf
	v_mov_b32_dpp v133, v207 row_ror:1 row_mask:0xf bank_mask:0xf
	v_mov_b32_dpp v153, v213 row_shr:2 row_mask:0xf bank_mask:0xf
	v_mov_b32_dpp v132, v212 row_shr:1 row_mask:0xf bank_mask:0xf
	v_mov_b32_dpp v133, v213 row_shr:1 row_mask:0xf bank_mask:0xf
	v_pk_mul_f32 v[152:153], v[106:107], v[152:153]
	v_pk_fma_f32 v[132:133], v[110:111], v[132:133], v[152:153]
; __device__ __forceinline__ float silu_f(float x) { return x * __builtin_amdgcn_rcpf(1.f + __expf(-x)); }
;     __device__ __forceinline__ void operator()(const f32x4 (&acc_c)[2][2][4][2], const Unit& u, int wr, int wc, int fr, int fq) const {
;     ...
;                 for (int m = 0; m < 4; ++m) {
;                     const f32x4 cg = acc[ai][0][m][n], cv = acc[ai][1][m][n];
;                     const f32x4 pg = m ? acc[ai][0][m - 1][n] : xpg, pv = m ? acc[ai][1][m - 1][n] : xpv;
;                     h16x4 o;
; #pragma unroll
;                     for (int e = 0; e < 4; ++e) {
;                         const float g1 = dppmov<0x111>(dppmov<0x121>(0.f, pg[e]), cg[e]), g2 = dppmov<0x112>(dppmov<0x122>(0.f, pg[e]), cg[e]);
;                         const float v1 = dppmov<0x111>(dppmov<0x121>(0.f, pv[e]), cv[e]), v2 = dppmov<0x112>(dppmov<0x122>(0.f, pv[e]), cv[e]);
;                         const float gate = wg[0][e] * g2 + wg[1][e] * g1 + wg[2][e] * cg[e] + bg[e];
;                         const float val = wv[0][e] * v2 + wv[1][e] * v1 + wv[2][e] * cv[e] + bv[e];
;                         o[e] = (h16)(silu_f(gate) * val);
;                     }
;                     *(h16x4*)(act + (size_t)(row0 + ai * HALF + m * 16) * FF + ch0 + 4 * n) = o;
	v_pk_fma_f32 v[132:133], v[212:213], v[114:115], v[132:133]
	v_pk_add_f32 v[132:133], v[118:119], v[132:133]
	v_mov_b32_dpp v206, v208 row_ror:2 row_mask:0xf bank_mask:0xf
	v_mul_f32_e32 v0, 0xbfb8aa3b, v132
	v_exp_f32_e32 v0, v0
	v_mul_f32_e32 v129, 0xbfb8aa3b, v133
	v_exp_f32_e32 v129, v129
	v_add_f32_e32 v0, 1.0, v0
	v_mov_b32_dpp v207, v209 row_ror:2 row_mask:0xf bank_mask:0xf
	v_rcp_f32_e32 v152, v0
	v_add_f32_e32 v0, 1.0, v129
	v_mov_b32_dpp v154, v208 row_ror:1 row_mask:0xf bank_mask:0xf
	v_mov_b32_dpp v206, v210 row_shr:2 row_mask:0xf bank_mask:0xf
	v_mov_b32_dpp v155, v209 row_ror:1 row_mask:0xf bank_mask:0xf
	v_mov_b32_dpp v207, v211 row_shr:2 row_mask:0xf bank_mask:0xf
	v_rcp_f32_e32 v153, v0
	v_mov_b32_dpp v154, v210 row_shr:1 row_mask:0xf bank_mask:0xf
	v_mov_b32_dpp v155, v211 row_shr:1 row_mask:0xf bank_mask:0xf
	v_pk_mul_f32 v[206:207], v[90:91], v[206:207]
	v_pk_mul_f32 v[132:133], v[132:133], v[152:153]
	v_pk_fma_f32 v[154:155], v[94:95], v[154:155], v[206:207]
	v_pk_fma_f32 v[154:155], v[210:211], v[98:99], v[154:155]
	v_pk_add_f32 v[154:155], v[102:103], v[154:155]
	v_mov_b32_dpp v206, v202 row_ror:2 row_mask:0xf bank_mask:0xf
	v_pk_mul_f32 v[132:133], v[154:155], v[132:133]
	v_cvt_pk_f16_f32 v152, v132, v133
	v_mov_b32_dpp v154, v200 row_ror:2 row_mask:0xf bank_mask:0xf
	v_mov_b32_dpp v155, v201 row_ror:2 row_mask:0xf bank_mask:0xf
	v_mov_b32_dpp v132, v200 row_ror:1 row_mask:0xf bank_mask:0xf
	v_mov_b32_dpp v154, v204 row_shr:2 row_mask:0xf bank_mask:0xf
	v_mov_b32_dpp v133, v201 row_ror:1 row_mask:0xf bank_mask:0xf
	v_mov_b32_dpp v155, v205 row_shr:2 row_mask:0xf bank_mask:0xf
	v_mov_b32_dpp v132, v204 row_shr:1 row_mask:0xf bank_mask:0xf
	v_mov_b32_dpp v133, v205 row_shr:1 row_mask:0xf bank_mask:0xf
	v_pk_mul_f32 v[154:155], v[108:109], v[154:155]
	v_pk_fma_f32 v[132:133], v[112:113], v[132:133], v[154:155]
	v_pk_fma_f32 v[132:133], v[204:205], v[116:117], v[132:133]
	v_mov_b32_dpp v207, v203 row_ror:2 row_mask:0xf bank_mask:0xf
	v_pk_add_f32 v[132:133], v[120:121], v[132:133]
	v_mov_b32_dpp v200, v202 row_ror:1 row_mask:0xf bank_mask:0xf
	v_mul_f32_e32 v0, 0xbfb8aa3b, v132
	v_exp_f32_e32 v0, v0
	v_mul_f32_e32 v129, 0xbfb8aa3b, v133
	v_exp_f32_e32 v129, v129
	v_mov_b32_dpp v206, v134 row_shr:2 row_mask:0xf bank_mask:0xf
	v_add_f32_e32 v0, 1.0, v0
	v_rcp_f32_e32 v154, v0
	v_add_f32_e32 v0, 1.0, v129
	v_mov_b32_dpp v201, v203 row_ror:1 row_mask:0xf bank_mask:0xf
	v_mov_b32_dpp v207, v135 row_shr:2 row_mask:0xf bank_mask:0xf
	v_rcp_f32_e32 v155, v0
	v_mov_b32_dpp v200, v134 row_shr:1 row_mask:0xf bank_mask:0xf
	v_mov_b32_dpp v201, v135 row_shr:1 row_mask:0xf bank_mask:0xf
	v_pk_mul_f32 v[202:203], v[92:93], v[206:207]
	v_pk_mul_f32 v[132:133], v[132:133], v[154:155]
	v_pk_fma_f32 v[200:201], v[96:97], v[200:201], v[202:203]
	v_pk_fma_f32 v[200:201], v[134:135], v[100:101], v[200:201]
	v_pk_add_f32 v[200:201], v[104:105], v[200:201]
	v_mov_b32_dpp v154, v212 row_ror:2 row_mask:0xf bank_mask:0xf
	v_pk_mul_f32 v[132:133], v[200:201], v[132:133]
	v_mov_b32_dpp v155, v213 row_ror:2 row_mask:0xf bank_mask:0xf
	v_cvt_pk_f16_f32 v153, v132, v133
	v_mad_i64_i32 v[132:133], s[4:5], v198, s41, v[148:149]
	v_lshl_add_u64 v[132:133], v[132:133], 0, v[150:151]
	global_store_dwordx2 v[132:133], v[152:153], off
	v_mov_b32_dpp v154, v136 row_shr:2 row_mask:0xf bank_mask:0xf
	v_mov_b32_dpp v152, v212 row_ror:1 row_mask:0xf bank_mask:0xf
	v_mov_b32_dpp v153, v213 row_ror:1 row_mask:0xf bank_mask:0xf
	v_mov_b32_dpp v155, v137 row_shr:2 row_mask:0xf bank_mask:0xf
	v_mov_b32_dpp v152, v136 row_shr:1 row_mask:0xf bank_mask:0xf
	v_mov_b32_dpp v153, v137 row_shr:1 row_mask:0xf bank_mask:0xf
	v_pk_mul_f32 v[154:155], v[106:107], v[154:155]
	v_pk_fma_f32 v[152:153], v[110:111], v[152:153], v[154:155]
	v_pk_fma_f32 v[152:153], v[136:137], v[114:115], v[152:153]
	v_pk_add_f32 v[152:153], v[118:119], v[152:153]
	v_mov_b32_dpp v200, v210 row_ror:2 row_mask:0xf bank_mask:0xf
	v_mul_f32_e32 v0, 0xbfb8aa3b, v152
	v_exp_f32_e32 v0, v0
	v_mul_f32_e32 v129, 0xbfb8aa3b, v153
	v_exp_f32_e32 v129, v129
	v_add_f32_e32 v0, 1.0, v0
	v_mov_b32_dpp v201, v211 row_ror:2 row_mask:0xf bank_mask:0xf
	v_rcp_f32_e32 v154, v0
	v_add_f32_e32 v0, 1.0, v129
	v_mov_b32_dpp v198, v210 row_ror:1 row_mask:0xf bank_mask:0xf
	v_mov_b32_dpp v200, v122 row_shr:2 row_mask:0xf bank_mask:0xf
	v_mov_b32_dpp v199, v211 row_ror:1 row_mask:0xf bank_mask:0xf
	v_mov_b32_dpp v201, v123 row_shr:2 row_mask:0xf bank_mask:0xf
	v_rcp_f32_e32 v155, v0
	v_mov_b32_dpp v198, v122 row_shr:1 row_mask:0xf bank_mask:0xf
	v_mov_b32_dpp v199, v123 row_shr:1 row_mask:0xf bank_mask:0xf
	v_pk_mul_f32 v[200:201], v[90:91], v[200:201]
	v_pk_mul_f32 v[152:153], v[152:153], v[154:155]
	v_pk_fma_f32 v[198:199], v[94:95], v[198:199], v[200:201]
	v_pk_fma_f32 v[198:199], v[122:123], v[98:99], v[198:199]
	v_pk_add_f32 v[198:199], v[102:103], v[198:199]
	v_mov_b32_dpp v154, v204 row_ror:1 row_mask:0xf bank_mask:0xf
	v_pk_mul_f32 v[152:153], v[198:199], v[152:153]
	v_mov_b32_dpp v198, v204 row_ror:2 row_mask:0xf bank_mask:0xf
	v_mov_b32_dpp v199, v205 row_ror:2 row_mask:0xf bank_mask:0xf
	s_nop 0
	v_mov_b32_dpp v198, v126 row_shr:2 row_mask:0xf bank_mask:0xf
	v_mov_b32_dpp v155, v205 row_ror:1 row_mask:0xf bank_mask:0xf
	v_mov_b32_dpp v199, v127 row_shr:2 row_mask:0xf bank_mask:0xf
	v_mov_b32_dpp v154, v126 row_shr:1 row_mask:0xf bank_mask:0xf
	v_mov_b32_dpp v200, v134 row_ror:1 row_mask:0xf bank_mask:0xf
	v_mov_b32_dpp v202, v134 row_ror:2 row_mask:0xf bank_mask:0xf
	v_mov_b32_dpp v155, v127 row_shr:1 row_mask:0xf bank_mask:0xf
	v_mov_b32_dpp v201, v135 row_ror:1 row_mask:0xf bank_mask:0xf
; #define LAS __attribute__((address_space(3)))
; __device__ __forceinline__ float silu_f(float x) { return x * __builtin_amdgcn_rcpf(1.f + __expf(-x)); }
;     __device__ __forceinline__ void operator()(const f32x4 (&acc_c)[2][2][4][2], const Unit& u, int wr, int wc, int fr, int fq) const {
;     ...
;             for (int ai = 0; ai < 2; ++ai) {
;                 f32x4 xpg = {0.f, 0.f, 0.f, 0.f}, xpv = {0.f, 0.f, 0.f, 0.f};
;                 const bool top = (ai == 0 && wr == 0);
;                 if (!top && fr >= 14) { const int ps = (wr == 1) ? ((ai * 2) * 4 + wc) : (((ai - 1) * 2 + 1) * 4 + wc);
;                     xpg = *(const LAS f32x4*)(xch + ps * 128 + (fr - 14) * 64 + 8 * fq + 4 * n); xpv = *(const LAS f32x4*)(xch + ps * 128 + (fr - 14) * 64 + 32 + 8 * fq + 4 * n); }
; #pragma unroll
;                 for (int m = 0; m < 4; ++m) {
;                     const f32x4 cg = acc[ai][0][m][n], cv = acc[ai][1][m][n];
;                     const f32x4 pg = m ? acc[ai][0][m - 1][n] : xpg, pv = m ? acc[ai][1][m - 1][n] : xpv;
;                     h16x4 o;
; #pragma unroll
;                     for (int e = 0; e < 4; ++e) {
;                         const float g1 = dppmov<0x111>(dppmov<0x121>(0.f, pg[e]), cg[e]), g2 = dppmov<0x112>(dppmov<0x122>(0.f, pg[e]), cg[e]);
;                         const float v1 = dppmov<0x111>(dppmov<0x121>(0.f, pv[e]), cv[e]), v2 = dppmov<0x112>(dppmov<0x122>(0.f, pv[e]), cv[e]);
;                         const float gate = wg[0][e] * g2 + wg[1][e] * g1 + wg[2][e] * cg[e] + bg[e];
;                         const float val = wv[0][e] * v2 + wv[1][e] * v1 + wv[2][e] * cv[e] + bv[e];
;                         o[e] = (h16)(silu_f(gate) * val);
;                     }
;                     *(h16x4*)(act + (size_t)(row0 + ai * HALF + m * 16) * FF + ch0 + 4 * n) = o;
	v_mov_b32_dpp v203, v135 row_ror:2 row_mask:0xf bank_mask:0xf
	v_pk_mul_f32 v[134:135], v[108:109], v[198:199]
	v_mov_b32_dpp v202, v124 row_shr:2 row_mask:0xf bank_mask:0xf
	v_pk_fma_f32 v[134:135], v[112:113], v[154:155], v[134:135]
	v_mov_b32_dpp v203, v125 row_shr:2 row_mask:0xf bank_mask:0xf
	v_pk_fma_f32 v[134:135], v[126:127], v[116:117], v[134:135]
	v_mov_b32_dpp v200, v124 row_shr:1 row_mask:0xf bank_mask:0xf
	v_pk_add_f32 v[134:135], v[120:121], v[134:135]
	v_mov_b32_dpp v201, v125 row_shr:1 row_mask:0xf bank_mask:0xf
	v_mul_f32_e32 v0, 0xbfb8aa3b, v134
	v_exp_f32_e32 v0, v0
	v_mul_f32_e32 v129, 0xbfb8aa3b, v135
	v_exp_f32_e32 v129, v129
	v_pk_mul_f32 v[198:199], v[92:93], v[202:203]
	v_add_f32_e32 v0, 1.0, v0
	v_rcp_f32_e32 v154, v0
	v_add_f32_e32 v0, 1.0, v129
	v_rcp_f32_e32 v155, v0
	v_pk_fma_f32 v[198:199], v[96:97], v[200:201], v[198:199]
	v_cvt_pk_f16_f32 v152, v152, v153
	v_pk_fma_f32 v[198:199], v[124:125], v[100:101], v[198:199]
	v_pk_mul_f32 v[134:135], v[134:135], v[154:155]
	v_pk_add_f32 v[198:199], v[104:105], v[198:199]
	v_pk_mul_f32 v[134:135], v[198:199], v[134:135]
	v_cvt_pk_f16_f32 v153, v134, v135
	v_mad_i64_i32 v[134:135], s[4:5], v196, s41, v[148:149]
	v_lshl_add_u64 v[134:135], v[134:135], 0, v[150:151]
	global_store_dwordx2 v[134:135], v[152:153], off
	v_mov_b32_dpp v154, v136 row_ror:2 row_mask:0xf bank_mask:0xf
	v_mov_b32_dpp v155, v137 row_ror:2 row_mask:0xf bank_mask:0xf
	v_mov_b32_dpp v152, v136 row_ror:1 row_mask:0xf bank_mask:0xf
	v_mov_b32_dpp v154, v142 row_shr:2 row_mask:0xf bank_mask:0xf
	v_mov_b32_dpp v153, v137 row_ror:1 row_mask:0xf bank_mask:0xf
	v_mov_b32_dpp v155, v143 row_shr:2 row_mask:0xf bank_mask:0xf
	v_mov_b32_dpp v152, v142 row_shr:1 row_mask:0xf bank_mask:0xf
	v_mov_b32_dpp v136, v122 row_ror:1 row_mask:0xf bank_mask:0xf
	v_mov_b32_dpp v196, v122 row_ror:2 row_mask:0xf bank_mask:0xf
	v_mov_b32_dpp v153, v143 row_shr:1 row_mask:0xf bank_mask:0xf
	v_mov_b32_dpp v137, v123 row_ror:1 row_mask:0xf bank_mask:0xf
	v_mov_b32_dpp v197, v123 row_ror:2 row_mask:0xf bank_mask:0xf
	v_pk_mul_f32 v[122:123], v[106:107], v[154:155]
	v_mov_b32_dpp v196, v138 row_shr:2 row_mask:0xf bank_mask:0xf
	v_pk_fma_f32 v[122:123], v[110:111], v[152:153], v[122:123]
	v_mov_b32_dpp v197, v139 row_shr:2 row_mask:0xf bank_mask:0xf
	v_pk_fma_f32 v[122:123], v[142:143], v[114:115], v[122:123]
	v_mov_b32_dpp v136, v138 row_shr:1 row_mask:0xf bank_mask:0xf
	v_pk_add_f32 v[122:123], v[118:119], v[122:123]
	v_mov_b32_dpp v137, v139 row_shr:1 row_mask:0xf bank_mask:0xf
	v_mul_f32_e32 v0, 0xbfb8aa3b, v122
	v_exp_f32_e32 v0, v0
	v_mul_f32_e32 v129, 0xbfb8aa3b, v123
	v_exp_f32_e32 v129, v129
	v_pk_mul_f32 v[152:153], v[90:91], v[196:197]
	v_add_f32_e32 v0, 1.0, v0
	v_rcp_f32_e32 v142, v0
	v_add_f32_e32 v0, 1.0, v129
	v_rcp_f32_e32 v143, v0
	v_pk_fma_f32 v[136:137], v[94:95], v[136:137], v[152:153]
	v_mov_b32_e32 v147, 0
	v_pk_fma_f32 v[136:137], v[138:139], v[98:99], v[136:137]
	v_pk_mul_f32 v[122:123], v[122:123], v[142:143]
	v_pk_add_f32 v[136:137], v[102:103], v[136:137]
	v_pk_mul_f32 v[122:123], v[136:137], v[122:123]
	v_mov_b32_dpp v138, v126 row_ror:2 row_mask:0xf bank_mask:0xf
	v_mov_b32_dpp v139, v127 row_ror:2 row_mask:0xf bank_mask:0xf
	v_mov_b32_dpp v136, v126 row_ror:1 row_mask:0xf bank_mask:0xf
	v_mov_b32_dpp v138, v144 row_shr:2 row_mask:0xf bank_mask:0xf
	v_mov_b32_dpp v137, v127 row_ror:1 row_mask:0xf bank_mask:0xf
	v_mov_b32_dpp v139, v145 row_shr:2 row_mask:0xf bank_mask:0xf
	v_mov_b32_dpp v136, v144 row_shr:1 row_mask:0xf bank_mask:0xf
	v_mov_b32_dpp v126, v124 row_ror:1 row_mask:0xf bank_mask:0xf
	v_mov_b32_dpp v142, v124 row_ror:2 row_mask:0xf bank_mask:0xf
	v_mov_b32_dpp v137, v145 row_shr:1 row_mask:0xf bank_mask:0xf
	v_mov_b32_dpp v127, v125 row_ror:1 row_mask:0xf bank_mask:0xf
	v_mov_b32_dpp v143, v125 row_ror:2 row_mask:0xf bank_mask:0xf
	v_pk_mul_f32 v[124:125], v[108:109], v[138:139]
	v_cvt_pk_f16_f32 v122, v122, v123
	v_pk_fma_f32 v[124:125], v[112:113], v[136:137], v[124:125]
	v_mov_b32_dpp v142, v140 row_shr:2 row_mask:0xf bank_mask:0xf
	v_pk_fma_f32 v[124:125], v[144:145], v[116:117], v[124:125]
	v_mov_b32_dpp v143, v141 row_shr:2 row_mask:0xf bank_mask:0xf
	v_pk_add_f32 v[124:125], v[120:121], v[124:125]
	v_mov_b32_dpp v126, v140 row_shr:1 row_mask:0xf bank_mask:0xf
	v_mul_f32_e32 v0, 0xbfb8aa3b, v124
	v_exp_f32_e32 v0, v0
	v_mul_f32_e32 v123, 0xbfb8aa3b, v125
	v_exp_f32_e32 v123, v123
	v_mov_b32_dpp v127, v141 row_shr:1 row_mask:0xf bank_mask:0xf
	v_add_f32_e32 v0, 1.0, v0
	v_rcp_f32_e32 v136, v0
	v_add_f32_e32 v0, 1.0, v123
	v_rcp_f32_e32 v137, v0
	v_pk_mul_f32 v[138:139], v[92:93], v[142:143]
	v_pk_mul_f32 v[124:125], v[124:125], v[136:137]
	v_pk_fma_f32 v[126:127], v[96:97], v[126:127], v[138:139]
	s_nop 0
	v_pk_fma_f32 v[126:127], v[140:141], v[100:101], v[126:127]
	s_nop 0
	v_pk_add_f32 v[126:127], v[104:105], v[126:127]
	s_nop 0
	v_pk_mul_f32 v[124:125], v[126:127], v[124:125]
	s_nop 0
	v_cvt_pk_f16_f32 v123, v124, v125
	v_mad_i64_i32 v[124:125], s[4:5], v194, s41, v[148:149]
	v_lshl_add_u64 v[136:137], v[124:125], 0, v[150:151]
	global_store_dwordx2 v[136:137], v[122:123], off
	v_mov_b32_e32 v148, 0
	v_mov_b32_e32 v149, 0
	v_mov_b32_e32 v122, 0
	v_mov_b32_e32 v123, 0
	v_mov_b32_e32 v124, 0
	v_mov_b32_e32 v125, 0
	s_and_saveexec_b64 s[4:5], s[6:7]
	s_movk_i32 s86, 0x1a00
	s_cbranch_execz .LBB0_1444
	ds_read_b128 v[146:149], v235
	ds_read_b128 v[122:125], v234
; #define LAS __attribute__((address_space(3)))
;     __device__ __forceinline__ void operator()(const f32x4 (&acc_c)[2][2][4][2], const Unit& u, int wr, int wc, int fr, int fq) const {
;     ...
;             for (int m = 0; m < 4; ++m) { const float rs = rsqrtf(rsv[ai][m] * (1.0f / 1024.0f) + EPS);
; #pragma unroll
;                 for (int bj = 0; bj < 2; ++bj)
; #pragma unroll
;                     for (int n = 0; n < 2; ++n) acc[ai][bj][m][n] *= rs; }
;         if (fr >= 14) {
; #pragma unroll
;             for (int ai = 0; ai < 2; ++ai)
; #pragma unroll
;                 for (int bj = 0; bj < 2; ++bj)
; #pragma unroll
;                     for (int n = 0; n < 2; ++n) *(LAS f32x4*)(xch + ((ai * 2 + wr) * 4 + wc) * 128 + (fr - 14) * 64 + bj * 32 + 8 * fq + 4 * n) = acc[ai][bj][3][n];
;         }
;         if ((wr == 1 && fr >= 14) || (wr == 0 && fr < 2)) {
;             const int ai = wr, m = wr ? 3 : 0, srow = wr ? (2 + fr - 14) : fr;
; #pragma unroll
;             for (int bj = 0; bj < 2; ++bj) { const f32x4 a = wr ? acc[1][bj][3][0] : acc[0][bj][0][0], b = wr ? acc[1][bj][3][1] : acc[0][bj][0][1];
;                 *(u32x4*)(sb + ((size_t)u.pm * 4 + srow) * FF2 + u.pn * 256 + bj * 128 + jl) = pack8(a, b); }
;             (void)ai; (void)m;
;         }
;         asm volatile("s_waitcnt lgkmcnt(0)" ::: "memory");
;         __builtin_amdgcn_s_barrier(); __builtin_amdgcn_s_barrier();
;         asm volatile("" ::: "memory");
; #pragma unroll
;         for (int n = 0; n < 2; ++n) {
;             f32x4 wg[3], wv[3], bg, bv;
; #pragma unroll
;             for (int t = 0; t < 3; ++t) { wg[t] = *(const f32x4*)(cw + t * FF2 + ch0 + 4 * n); wv[t] = *(const f32x4*)(cw + t * FF2 + FF + ch0 + 4 * n); }
;             bg = *(const f32x4*)(cb + ch0 + 4 * n); bv = *(const f32x4*)(cb + FF + ch0 + 4 * n);
; #pragma unroll
;             for (int ai = 0; ai < 2; ++ai) {
;                 f32x4 xpg = {0.f, 0.f, 0.f, 0.f}, xpv = {0.f, 0.f, 0.f, 0.f};
;                 const bool top = (ai == 0 && wr == 0);
;                 if (!top && fr >= 14) { const int ps = (wr == 1) ? ((ai * 2) * 4 + wc) : (((ai - 1) * 2 + 1) * 4 + wc);
;                     xpg = *(const LAS f32x4*)(xch + ps * 128 + (fr - 14) * 64 + 8 * fq + 4 * n); xpv = *(const LAS f32x4*)(xch + ps * 128 + (fr - 14) * 64 + 32 + 8 * fq + 4 * n); }
; #pragma unroll
;                 for (int m = 0; m < 4; ++m) {
.LBB0_1444:
	s_or_b64 exec, exec, s[4:5]
	v_fmamk_f32 v0, v195, 0x3a800000, v216
	v_mul_f32_e32 v126, 0x4b800000, v0
	v_cmp_gt_f32_e32 vcc, s2, v0
	v_add_u32_e32 v139, 0x90, v192
	v_add_u32_e32 v141, 0xa0, v192
	v_cndmask_b32_e32 v0, v0, v126, vcc
	v_rsq_f32_e32 v126, v0
	v_add_u32_e32 v129, 0x80, v192
	v_add_u32_e32 v0, 0xb0, v192
	v_mul_f32_e32 v127, 0x45800000, v126
	v_cndmask_b32_e32 v138, v126, v127, vcc
	v_fmamk_f32 v126, v193, 0x3a800000, v216
	v_mul_f32_e32 v127, 0x4b800000, v126
	v_cmp_gt_f32_e32 vcc, s2, v126
	v_pk_mul_f32 v[144:145], v[78:79], v[138:139] op_sel_hi:[1,0]
	v_pk_mul_f32 v[78:79], v[72:73], v[138:139] op_sel_hi:[1,0]
	v_cndmask_b32_e32 v126, v126, v127, vcc
	v_rsq_f32_e32 v126, v126
	v_pk_mul_f32 v[152:153], v[70:71], v[138:139] op_sel_hi:[1,0]
	v_fmamk_f32 v72, v191, 0x3a800000, v216
	v_mul_f32_e32 v73, 0x4b800000, v72
	v_mul_f32_e32 v70, 0x45800000, v126
	v_cndmask_b32_e32 v140, v126, v70, vcc
	v_cmp_gt_f32_e32 vcc, s2, v72
	v_pk_mul_f32 v[70:71], v[76:77], v[140:141] op_sel_hi:[1,0]
	v_pk_mul_f32 v[76:77], v[74:75], v[140:141] op_sel_hi:[1,0]
	v_cndmask_b32_e32 v72, v72, v73, vcc
	v_rsq_f32_e32 v126, v72
	v_pk_mul_f32 v[74:75], v[62:63], v[140:141] op_sel_hi:[1,0]
	v_pk_mul_f32 v[72:73], v[64:65], v[140:141] op_sel_hi:[1,0]
	v_mul_f32_e32 v62, 0x45800000, v126
	v_cndmask_b32_e32 v142, v126, v62, vcc
	v_pk_mul_f32 v[62:63], v[68:69], v[142:143] op_sel_hi:[1,0]
	v_pk_mul_f32 v[64:65], v[66:67], v[142:143] op_sel_hi:[1,0]
	s_waitcnt lgkmcnt(1)
	v_mov_b32_dpp v68, v146 row_ror:2 row_mask:0xf bank_mask:0xf
	v_mov_b32_dpp v69, v147 row_ror:2 row_mask:0xf bank_mask:0xf
	v_mov_b32_dpp v66, v146 row_ror:1 row_mask:0xf bank_mask:0xf
	v_mov_b32_dpp v68, v144 row_shr:2 row_mask:0xf bank_mask:0xf
	v_mov_b32_dpp v67, v147 row_ror:1 row_mask:0xf bank_mask:0xf
	v_mov_b32_dpp v69, v145 row_shr:2 row_mask:0xf bank_mask:0xf
	v_mov_b32_dpp v66, v144 row_shr:1 row_mask:0xf bank_mask:0xf
	v_mov_b32_dpp v67, v145 row_shr:1 row_mask:0xf bank_mask:0xf
	v_pk_mul_f32 v[68:69], v[106:107], v[68:69]
	v_pk_fma_f32 v[66:67], v[110:111], v[66:67], v[68:69]
	v_pk_fma_f32 v[66:67], v[144:145], v[114:115], v[66:67]
	v_pk_add_f32 v[66:67], v[118:119], v[66:67]
	s_waitcnt lgkmcnt(0)
	v_mov_b32_dpp v146, v122 row_ror:2 row_mask:0xf bank_mask:0xf
	v_mul_f32_e32 v68, 0xbfb8aa3b, v66
	v_mul_f32_e32 v69, 0xbfb8aa3b, v67
	v_exp_f32_e32 v68, v68
	v_exp_f32_e32 v69, v69
	v_mov_b32_dpp v147, v123 row_ror:2 row_mask:0xf bank_mask:0xf
	v_mov_b32_dpp v126, v122 row_ror:1 row_mask:0xf bank_mask:0xf
	v_add_f32_e32 v68, 1.0, v68
	v_add_f32_e32 v69, 1.0, v69
	v_mov_b32_dpp v146, v152 row_shr:2 row_mask:0xf bank_mask:0xf
	v_mov_b32_dpp v127, v123 row_ror:1 row_mask:0xf bank_mask:0xf
	v_mov_b32_dpp v147, v153 row_shr:2 row_mask:0xf bank_mask:0xf
	v_rcp_f32_e32 v68, v68
	v_rcp_f32_e32 v69, v69
	v_mov_b32_dpp v126, v152 row_shr:1 row_mask:0xf bank_mask:0xf
	v_mov_b32_dpp v127, v153 row_shr:1 row_mask:0xf bank_mask:0xf
	v_pk_mul_f32 v[122:123], v[90:91], v[146:147]
	v_pk_mul_f32 v[66:67], v[66:67], v[68:69]
	v_pk_fma_f32 v[122:123], v[94:95], v[126:127], v[122:123]
	v_pk_mul_f32 v[80:81], v[80:81], v[138:139] op_sel_hi:[1,0]
	v_pk_fma_f32 v[122:123], v[152:153], v[98:99], v[122:123]
	v_pk_add_f32 v[122:123], v[102:103], v[122:123]
	v_pk_mul_f32 v[66:67], v[122:123], v[66:67]
	v_cvt_pk_f16_f32 v68, v66, v67
	v_mov_b32_dpp v122, v148 row_ror:2 row_mask:0xf bank_mask:0xf
	v_mov_b32_dpp v123, v149 row_ror:2 row_mask:0xf bank_mask:0xf
	v_mov_b32_dpp v66, v148 row_ror:1 row_mask:0xf bank_mask:0xf
	v_mov_b32_dpp v122, v80 row_shr:2 row_mask:0xf bank_mask:0xf
	v_mov_b32_dpp v67, v149 row_ror:1 row_mask:0xf bank_mask:0xf
	v_mov_b32_dpp v123, v81 row_shr:2 row_mask:0xf bank_mask:0xf
	v_mov_b32_dpp v66, v80 row_shr:1 row_mask:0xf bank_mask:0xf
	v_mov_b32_dpp v67, v81 row_shr:1 row_mask:0xf bank_mask:0xf
	v_pk_mul_f32 v[122:123], v[108:109], v[122:123]
	v_pk_fma_f32 v[66:67], v[112:113], v[66:67], v[122:123]
	v_mov_b32_dpp v146, v124 row_ror:2 row_mask:0xf bank_mask:0xf
	v_pk_fma_f32 v[66:67], v[80:81], v[116:117], v[66:67]
	v_pk_add_f32 v[66:67], v[120:121], v[66:67]
	v_mov_b32_dpp v147, v125 row_ror:2 row_mask:0xf bank_mask:0xf
	v_mul_f32_e32 v69, 0xbfb8aa3b, v66
	v_exp_f32_e32 v69, v69
	v_mul_f32_e32 v122, 0xbfb8aa3b, v67
	v_exp_f32_e32 v123, v122
	v_mov_b32_dpp v126, v124 row_ror:1 row_mask:0xf bank_mask:0xf
	v_add_f32_e32 v69, 1.0, v69
	v_rcp_f32_e32 v122, v69
	v_add_f32_e32 v69, 1.0, v123
	v_mov_b32_dpp v146, v78 row_shr:2 row_mask:0xf bank_mask:0xf
	v_mov_b32_dpp v127, v125 row_ror:1 row_mask:0xf bank_mask:0xf
	v_mov_b32_dpp v147, v79 row_shr:2 row_mask:0xf bank_mask:0xf
	v_rcp_f32_e32 v123, v69
	v_mov_b32_dpp v126, v78 row_shr:1 row_mask:0xf bank_mask:0xf
	v_mov_b32_dpp v127, v79 row_shr:1 row_mask:0xf bank_mask:0xf
	v_pk_mul_f32 v[124:125], v[92:93], v[146:147]
	v_pk_mul_f32 v[66:67], v[66:67], v[122:123]
	v_pk_fma_f32 v[124:125], v[96:97], v[126:127], v[124:125]
	v_pk_mul_f32 v[58:59], v[58:59], v[142:143] op_sel_hi:[1,0]
	v_pk_fma_f32 v[124:125], v[78:79], v[100:101], v[124:125]
	v_pk_mul_f32 v[60:61], v[60:61], v[142:143] op_sel_hi:[1,0]
	v_pk_add_f32 v[124:125], v[104:105], v[124:125]
	s_nop 0
	v_pk_mul_f32 v[66:67], v[124:125], v[66:67]
	v_cvt_pk_f16_f32 v69, v66, v67
	v_mov_b64_e32 v[66:67], s[12:13]
	v_mad_i64_i32 v[122:123], s[4:5], v129, s41, v[66:67]
	v_lshl_add_u64 v[126:127], v[122:123], 0, v[150:151]
	global_store_dwordx2 v[126:127], v[68:69], off
	v_mov_b32_dpp v122, v144 row_ror:2 row_mask:0xf bank_mask:0xf
	v_mov_b32_dpp v123, v145 row_ror:2 row_mask:0xf bank_mask:0xf
	v_mov_b32_dpp v68, v144 row_ror:1 row_mask:0xf bank_mask:0xf
; __device__ __forceinline__ float silu_f(float x) { return x * __builtin_amdgcn_rcpf(1.f + __expf(-x)); }
;     __device__ __forceinline__ void operator()(const f32x4 (&acc_c)[2][2][4][2], const Unit& u, int wr, int wc, int fr, int fq) const {
;     ...
;                 for (int m = 0; m < 4; ++m) {
;                     const f32x4 cg = acc[ai][0][m][n], cv = acc[ai][1][m][n];
;                     const f32x4 pg = m ? acc[ai][0][m - 1][n] : xpg, pv = m ? acc[ai][1][m - 1][n] : xpv;
;                     h16x4 o;
; #pragma unroll
;                     for (int e = 0; e < 4; ++e) {
;                         const float g1 = dppmov<0x111>(dppmov<0x121>(0.f, pg[e]), cg[e]), g2 = dppmov<0x112>(dppmov<0x122>(0.f, pg[e]), cg[e]);
;                         const float v1 = dppmov<0x111>(dppmov<0x121>(0.f, pv[e]), cv[e]), v2 = dppmov<0x112>(dppmov<0x122>(0.f, pv[e]), cv[e]);
;                         const float gate = wg[0][e] * g2 + wg[1][e] * g1 + wg[2][e] * cg[e] + bg[e];
;                         const float val = wv[0][e] * v2 + wv[1][e] * v1 + wv[2][e] * cv[e] + bv[e];
;                         o[e] = (h16)(silu_f(gate) * val);
;                     }
;                     *(h16x4*)(act + (size_t)(row0 + ai * HALF + m * 16) * FF + ch0 + 4 * n) = o;
	v_mov_b32_dpp v122, v76 row_shr:2 row_mask:0xf bank_mask:0xf
	v_mov_b32_dpp v69, v145 row_ror:1 row_mask:0xf bank_mask:0xf
	v_mov_b32_dpp v123, v77 row_shr:2 row_mask:0xf bank_mask:0xf
	v_mov_b32_dpp v68, v76 row_shr:1 row_mask:0xf bank_mask:0xf
	v_mov_b32_dpp v69, v77 row_shr:1 row_mask:0xf bank_mask:0xf
	v_pk_mul_f32 v[122:123], v[106:107], v[122:123]
	v_pk_fma_f32 v[68:69], v[110:111], v[68:69], v[122:123]
	v_pk_fma_f32 v[68:69], v[76:77], v[114:115], v[68:69]
	v_mov_b32_dpp v144, v152 row_ror:2 row_mask:0xf bank_mask:0xf
	v_pk_add_f32 v[68:69], v[118:119], v[68:69]
	v_mul_f32_e32 v122, 0xbfb8aa3b, v68
	v_mul_f32_e32 v123, 0xbfb8aa3b, v69
	v_exp_f32_e32 v122, v122
	v_exp_f32_e32 v123, v123
	v_mov_b32_dpp v145, v153 row_ror:2 row_mask:0xf bank_mask:0xf
	v_mov_b32_dpp v124, v152 row_ror:1 row_mask:0xf bank_mask:0xf
	v_add_f32_e32 v122, 1.0, v122
	v_add_f32_e32 v123, 1.0, v123
	v_mov_b32_dpp v144, v74 row_shr:2 row_mask:0xf bank_mask:0xf
	v_mov_b32_dpp v125, v153 row_ror:1 row_mask:0xf bank_mask:0xf
	v_mov_b32_dpp v145, v75 row_shr:2 row_mask:0xf bank_mask:0xf
	v_rcp_f32_e32 v122, v122
	v_rcp_f32_e32 v123, v123
	v_mov_b32_dpp v124, v74 row_shr:1 row_mask:0xf bank_mask:0xf
	v_mov_b32_dpp v125, v75 row_shr:1 row_mask:0xf bank_mask:0xf
	v_pk_mul_f32 v[144:145], v[90:91], v[144:145]
	v_pk_mul_f32 v[68:69], v[68:69], v[122:123]
	v_pk_fma_f32 v[124:125], v[94:95], v[124:125], v[144:145]
	v_pk_fma_f32 v[124:125], v[74:75], v[98:99], v[124:125]
	v_pk_add_f32 v[124:125], v[102:103], v[124:125]
	v_mov_b32_dpp v122, v80 row_ror:1 row_mask:0xf bank_mask:0xf
	v_pk_mul_f32 v[68:69], v[124:125], v[68:69]
	v_mov_b32_dpp v124, v80 row_ror:2 row_mask:0xf bank_mask:0xf
	v_mov_b32_dpp v125, v81 row_ror:2 row_mask:0xf bank_mask:0xf
	s_nop 0
	v_mov_b32_dpp v124, v70 row_shr:2 row_mask:0xf bank_mask:0xf
	v_mov_b32_dpp v123, v81 row_ror:1 row_mask:0xf bank_mask:0xf
	v_mov_b32_dpp v125, v71 row_shr:2 row_mask:0xf bank_mask:0xf
	v_mov_b32_dpp v122, v70 row_shr:1 row_mask:0xf bank_mask:0xf
	v_mov_b32_dpp v80, v78 row_ror:1 row_mask:0xf bank_mask:0xf
	v_mov_b32_dpp v144, v78 row_ror:2 row_mask:0xf bank_mask:0xf
	v_mov_b32_dpp v123, v71 row_shr:1 row_mask:0xf bank_mask:0xf
	v_mov_b32_dpp v81, v79 row_ror:1 row_mask:0xf bank_mask:0xf
	v_mov_b32_dpp v145, v79 row_ror:2 row_mask:0xf bank_mask:0xf
	v_pk_mul_f32 v[78:79], v[108:109], v[124:125]
	v_cvt_pk_f16_f32 v68, v68, v69
	v_pk_fma_f32 v[78:79], v[112:113], v[122:123], v[78:79]
	v_mov_b32_dpp v144, v72 row_shr:2 row_mask:0xf bank_mask:0xf
	v_pk_fma_f32 v[78:79], v[70:71], v[116:117], v[78:79]
	v_mov_b32_dpp v145, v73 row_shr:2 row_mask:0xf bank_mask:0xf
	v_pk_add_f32 v[78:79], v[120:121], v[78:79]
	v_mov_b32_dpp v80, v72 row_shr:1 row_mask:0xf bank_mask:0xf
	v_mul_f32_e32 v69, 0xbfb8aa3b, v78
	v_exp_f32_e32 v69, v69
	v_mul_f32_e32 v122, 0xbfb8aa3b, v79
	v_exp_f32_e32 v123, v122
	v_mov_b32_dpp v81, v73 row_shr:1 row_mask:0xf bank_mask:0xf
	v_add_f32_e32 v69, 1.0, v69
	v_rcp_f32_e32 v122, v69
	v_add_f32_e32 v69, 1.0, v123
	v_rcp_f32_e32 v123, v69
	v_pk_mul_f32 v[124:125], v[92:93], v[144:145]
	v_pk_mul_f32 v[78:79], v[78:79], v[122:123]
	v_pk_fma_f32 v[80:81], v[96:97], v[80:81], v[124:125]
	s_nop 0
	v_pk_fma_f32 v[80:81], v[72:73], v[100:101], v[80:81]
	s_nop 0
	v_pk_add_f32 v[80:81], v[104:105], v[80:81]
	s_nop 0
	v_pk_mul_f32 v[78:79], v[80:81], v[78:79]
	v_cvt_pk_f16_f32 v69, v78, v79
	v_mad_i64_i32 v[78:79], s[4:5], v139, s41, v[66:67]
	v_lshl_add_u64 v[124:125], v[78:79], 0, v[150:151]
	global_store_dwordx2 v[124:125], v[68:69], off
	v_mov_b32_dpp v78, v76 row_ror:2 row_mask:0xf bank_mask:0xf
	v_mov_b32_dpp v79, v77 row_ror:2 row_mask:0xf bank_mask:0xf
	v_mov_b32_dpp v68, v76 row_ror:1 row_mask:0xf bank_mask:0xf
	v_mov_b32_dpp v78, v64 row_shr:2 row_mask:0xf bank_mask:0xf
	v_mov_b32_dpp v69, v77 row_ror:1 row_mask:0xf bank_mask:0xf
	v_mov_b32_dpp v79, v65 row_shr:2 row_mask:0xf bank_mask:0xf
	v_mov_b32_dpp v68, v64 row_shr:1 row_mask:0xf bank_mask:0xf
	v_mov_b32_dpp v76, v74 row_ror:1 row_mask:0xf bank_mask:0xf
	v_mov_b32_dpp v80, v74 row_ror:2 row_mask:0xf bank_mask:0xf
	v_mov_b32_dpp v69, v65 row_shr:1 row_mask:0xf bank_mask:0xf
	v_mov_b32_dpp v77, v75 row_ror:1 row_mask:0xf bank_mask:0xf
	v_mov_b32_dpp v81, v75 row_ror:2 row_mask:0xf bank_mask:0xf
	v_pk_mul_f32 v[74:75], v[106:107], v[78:79]
	v_mov_b32_dpp v80, v58 row_shr:2 row_mask:0xf bank_mask:0xf
	v_pk_fma_f32 v[68:69], v[110:111], v[68:69], v[74:75]
	v_mov_b32_dpp v81, v59 row_shr:2 row_mask:0xf bank_mask:0xf
	v_pk_fma_f32 v[68:69], v[64:65], v[114:115], v[68:69]
	v_mov_b32_dpp v76, v58 row_shr:1 row_mask:0xf bank_mask:0xf
	v_pk_add_f32 v[68:69], v[118:119], v[68:69]
	v_mov_b32_dpp v77, v59 row_shr:1 row_mask:0xf bank_mask:0xf
	v_mul_f32_e32 v74, 0xbfb8aa3b, v68
	v_mul_f32_e32 v75, 0xbfb8aa3b, v69
	v_exp_f32_e32 v74, v74
	v_exp_f32_e32 v75, v75
	v_pk_mul_f32 v[78:79], v[90:91], v[80:81]
	v_add_f32_e32 v74, 1.0, v74
	v_add_f32_e32 v75, 1.0, v75
	v_rcp_f32_e32 v74, v74
	v_rcp_f32_e32 v75, v75
	v_pk_fma_f32 v[76:77], v[94:95], v[76:77], v[78:79]
	v_pk_fma_f32 v[76:77], v[58:59], v[98:99], v[76:77]
	v_pk_mul_f32 v[68:69], v[68:69], v[74:75]
	v_pk_add_f32 v[76:77], v[102:103], v[76:77]
	v_pk_mul_f32 v[68:69], v[76:77], v[68:69]
	s_nop 0
	v_mov_b32_dpp v76, v70 row_ror:2 row_mask:0xf bank_mask:0xf
	v_mov_b32_dpp v77, v71 row_ror:2 row_mask:0xf bank_mask:0xf
	v_mov_b32_dpp v74, v70 row_ror:1 row_mask:0xf bank_mask:0xf
	v_mov_b32_dpp v76, v62 row_shr:2 row_mask:0xf bank_mask:0xf
	v_mov_b32_dpp v75, v71 row_ror:1 row_mask:0xf bank_mask:0xf
	v_mov_b32_dpp v77, v63 row_shr:2 row_mask:0xf bank_mask:0xf
	v_mov_b32_dpp v74, v62 row_shr:1 row_mask:0xf bank_mask:0xf
; #define LAS __attribute__((address_space(3)))
; __device__ __forceinline__ float silu_f(float x) { return x * __builtin_amdgcn_rcpf(1.f + __expf(-x)); }
;     __device__ __forceinline__ void operator()(const f32x4 (&acc_c)[2][2][4][2], const Unit& u, int wr, int wc, int fr, int fq) const {
;     ...
;             f32x4 wg[3], wv[3], bg, bv;
; #pragma unroll
;             for (int t = 0; t < 3; ++t) { wg[t] = *(const f32x4*)(cw + t * FF2 + ch0 + 4 * n); wv[t] = *(const f32x4*)(cw + t * FF2 + FF + ch0 + 4 * n); }
;             bg = *(const f32x4*)(cb + ch0 + 4 * n); bv = *(const f32x4*)(cb + FF + ch0 + 4 * n);
; #pragma unroll
;             for (int ai = 0; ai < 2; ++ai) {
;                 f32x4 xpg = {0.f, 0.f, 0.f, 0.f}, xpv = {0.f, 0.f, 0.f, 0.f};
;                 const bool top = (ai == 0 && wr == 0);
;                 if (!top && fr >= 14) { const int ps = (wr == 1) ? ((ai * 2) * 4 + wc) : (((ai - 1) * 2 + 1) * 4 + wc);
;                     xpg = *(const LAS f32x4*)(xch + ps * 128 + (fr - 14) * 64 + 8 * fq + 4 * n); xpv = *(const LAS f32x4*)(xch + ps * 128 + (fr - 14) * 64 + 32 + 8 * fq + 4 * n); }
; #pragma unroll
;                 for (int m = 0; m < 4; ++m) {
;                     const f32x4 cg = acc[ai][0][m][n], cv = acc[ai][1][m][n];
;                     const f32x4 pg = m ? acc[ai][0][m - 1][n] : xpg, pv = m ? acc[ai][1][m - 1][n] : xpv;
;                     h16x4 o;
; #pragma unroll
;                     for (int e = 0; e < 4; ++e) {
;                         const float g1 = dppmov<0x111>(dppmov<0x121>(0.f, pg[e]), cg[e]), g2 = dppmov<0x112>(dppmov<0x122>(0.f, pg[e]), cg[e]);
;                         const float v1 = dppmov<0x111>(dppmov<0x121>(0.f, pv[e]), cv[e]), v2 = dppmov<0x112>(dppmov<0x122>(0.f, pv[e]), cv[e]);
;                         const float gate = wg[0][e] * g2 + wg[1][e] * g1 + wg[2][e] * cg[e] + bg[e];
;                         const float val = wv[0][e] * v2 + wv[1][e] * v1 + wv[2][e] * cv[e] + bv[e];
;                         o[e] = (h16)(silu_f(gate) * val);
;                     }
;                     *(h16x4*)(act + (size_t)(row0 + ai * HALF + m * 16) * FF + ch0 + 4 * n) = o;
;                 }
	v_mov_b32_dpp v70, v72 row_ror:1 row_mask:0xf bank_mask:0xf
	v_mov_b32_dpp v78, v72 row_ror:2 row_mask:0xf bank_mask:0xf
	v_mov_b32_dpp v75, v63 row_shr:1 row_mask:0xf bank_mask:0xf
	v_mov_b32_dpp v71, v73 row_ror:1 row_mask:0xf bank_mask:0xf
	v_mov_b32_dpp v79, v73 row_ror:2 row_mask:0xf bank_mask:0xf
	v_pk_mul_f32 v[72:73], v[108:109], v[76:77]
	v_cvt_pk_f16_f32 v68, v68, v69
	v_pk_fma_f32 v[72:73], v[112:113], v[74:75], v[72:73]
	v_mov_b32_dpp v78, v60 row_shr:2 row_mask:0xf bank_mask:0xf
	v_pk_fma_f32 v[72:73], v[62:63], v[116:117], v[72:73]
	v_mov_b32_dpp v79, v61 row_shr:2 row_mask:0xf bank_mask:0xf
	v_pk_add_f32 v[72:73], v[120:121], v[72:73]
	v_mov_b32_dpp v70, v60 row_shr:1 row_mask:0xf bank_mask:0xf
	v_mul_f32_e32 v69, 0xbfb8aa3b, v72
	v_exp_f32_e32 v69, v69
	v_mul_f32_e32 v74, 0xbfb8aa3b, v73
	v_exp_f32_e32 v75, v74
	v_mov_b32_dpp v71, v61 row_shr:1 row_mask:0xf bank_mask:0xf
	v_add_f32_e32 v69, 1.0, v69
	v_rcp_f32_e32 v74, v69
	v_add_f32_e32 v69, 1.0, v75
	v_rcp_f32_e32 v75, v69
	v_pk_mul_f32 v[76:77], v[92:93], v[78:79]
	v_pk_mul_f32 v[72:73], v[72:73], v[74:75]
	v_pk_fma_f32 v[70:71], v[96:97], v[70:71], v[76:77]
	s_nop 0
	v_pk_fma_f32 v[70:71], v[60:61], v[100:101], v[70:71]
	s_nop 0
	v_pk_add_f32 v[70:71], v[104:105], v[70:71]
	s_nop 0
	v_pk_mul_f32 v[70:71], v[70:71], v[72:73]
	v_cvt_pk_f16_f32 v69, v70, v71
	v_mad_i64_i32 v[70:71], s[4:5], v141, s41, v[66:67]
	v_lshl_add_u64 v[122:123], v[70:71], 0, v[150:151]
	global_store_dwordx2 v[122:123], v[68:69], off
	v_mov_b32_dpp v70, v64 row_ror:2 row_mask:0xf bank_mask:0xf
	v_mov_b32_dpp v71, v65 row_ror:2 row_mask:0xf bank_mask:0xf
	v_mov_b32_dpp v68, v64 row_ror:1 row_mask:0xf bank_mask:0xf
	v_mov_b32_dpp v70, v86 row_shr:2 row_mask:0xf bank_mask:0xf
	v_mov_b32_dpp v69, v65 row_ror:1 row_mask:0xf bank_mask:0xf
	v_mov_b32_dpp v71, v87 row_shr:2 row_mask:0xf bank_mask:0xf
	v_mov_b32_dpp v68, v86 row_shr:1 row_mask:0xf bank_mask:0xf
	v_mov_b32_dpp v64, v58 row_ror:1 row_mask:0xf bank_mask:0xf
	v_mov_b32_dpp v72, v58 row_ror:2 row_mask:0xf bank_mask:0xf
	v_mov_b32_dpp v69, v87 row_shr:1 row_mask:0xf bank_mask:0xf
	v_mov_b32_dpp v65, v59 row_ror:1 row_mask:0xf bank_mask:0xf
	v_mov_b32_dpp v73, v59 row_ror:2 row_mask:0xf bank_mask:0xf
	v_pk_mul_f32 v[58:59], v[106:107], v[70:71]
	v_mov_b32_dpp v72, v82 row_shr:2 row_mask:0xf bank_mask:0xf
	v_pk_fma_f32 v[58:59], v[110:111], v[68:69], v[58:59]
	v_mov_b32_dpp v73, v83 row_shr:2 row_mask:0xf bank_mask:0xf
	v_pk_fma_f32 v[58:59], v[86:87], v[114:115], v[58:59]
	v_mov_b32_dpp v64, v82 row_shr:1 row_mask:0xf bank_mask:0xf
	v_pk_add_f32 v[58:59], v[118:119], v[58:59]
	v_mov_b32_dpp v65, v83 row_shr:1 row_mask:0xf bank_mask:0xf
	v_mul_f32_e32 v68, 0xbfb8aa3b, v58
	v_mul_f32_e32 v69, 0xbfb8aa3b, v59
	v_exp_f32_e32 v68, v68
	v_exp_f32_e32 v69, v69
	v_pk_mul_f32 v[70:71], v[90:91], v[72:73]
	v_mov_b32_e32 v90, 0
	v_add_f32_e32 v68, 1.0, v68
	v_add_f32_e32 v69, 1.0, v69
	v_rcp_f32_e32 v68, v68
	v_rcp_f32_e32 v69, v69
	v_pk_fma_f32 v[64:65], v[94:95], v[64:65], v[70:71]
	v_pk_fma_f32 v[64:65], v[82:83], v[98:99], v[64:65]
	v_pk_mul_f32 v[58:59], v[58:59], v[68:69]
	v_pk_add_f32 v[64:65], v[102:103], v[64:65]
	v_pk_mul_f32 v[58:59], v[64:65], v[58:59]
	v_mov_b32_dpp v68, v62 row_ror:2 row_mask:0xf bank_mask:0xf
	v_mov_b32_dpp v69, v63 row_ror:2 row_mask:0xf bank_mask:0xf
	v_mov_b32_dpp v64, v62 row_ror:1 row_mask:0xf bank_mask:0xf
	v_mov_b32_dpp v68, v88 row_shr:2 row_mask:0xf bank_mask:0xf
	v_mov_b32_dpp v65, v63 row_ror:1 row_mask:0xf bank_mask:0xf
	v_mov_b32_dpp v69, v89 row_shr:2 row_mask:0xf bank_mask:0xf
	v_mov_b32_dpp v64, v88 row_shr:1 row_mask:0xf bank_mask:0xf
	v_mov_b32_dpp v62, v60 row_ror:1 row_mask:0xf bank_mask:0xf
	v_mov_b32_dpp v70, v60 row_ror:2 row_mask:0xf bank_mask:0xf
	v_mov_b32_dpp v65, v89 row_shr:1 row_mask:0xf bank_mask:0xf
	v_mov_b32_dpp v63, v61 row_ror:1 row_mask:0xf bank_mask:0xf
	v_mov_b32_dpp v71, v61 row_ror:2 row_mask:0xf bank_mask:0xf
	v_pk_mul_f32 v[60:61], v[108:109], v[68:69]
	v_cvt_pk_f16_f32 v58, v58, v59
	v_pk_fma_f32 v[60:61], v[112:113], v[64:65], v[60:61]
	v_mov_b32_dpp v70, v84 row_shr:2 row_mask:0xf bank_mask:0xf
	v_pk_fma_f32 v[60:61], v[88:89], v[116:117], v[60:61]
	v_mov_b32_dpp v71, v85 row_shr:2 row_mask:0xf bank_mask:0xf
	v_pk_add_f32 v[60:61], v[120:121], v[60:61]
	v_mov_b32_dpp v62, v84 row_shr:1 row_mask:0xf bank_mask:0xf
	v_mul_f32_e32 v59, 0xbfb8aa3b, v60
	v_exp_f32_e32 v59, v59
	v_mul_f32_e32 v64, 0xbfb8aa3b, v61
	v_exp_f32_e32 v65, v64
	v_mov_b32_dpp v63, v85 row_shr:1 row_mask:0xf bank_mask:0xf
	v_add_f32_e32 v59, 1.0, v59
	v_rcp_f32_e32 v64, v59
	v_add_f32_e32 v59, 1.0, v65
	v_rcp_f32_e32 v65, v59
	v_pk_mul_f32 v[68:69], v[92:93], v[70:71]
	v_mov_b32_e32 v98, 0
	v_pk_fma_f32 v[62:63], v[96:97], v[62:63], v[68:69]
	v_pk_mul_f32 v[60:61], v[60:61], v[64:65]
	v_pk_fma_f32 v[62:63], v[84:85], v[100:101], v[62:63]
	v_mov_b32_e32 v96, 0
	v_pk_add_f32 v[62:63], v[104:105], v[62:63]
	v_mov_b32_e32 v97, 0
	v_pk_mul_f32 v[60:61], v[62:63], v[60:61]
	v_add_co_u32_e32 v62, vcc, s95, v186
	v_cvt_pk_f16_f32 v59, v60, v61
	s_nop 0
	v_addc_co_u32_e32 v63, vcc, 0, v187, vcc
	v_mad_i64_i32 v[60:61], s[4:5], v0, s41, v[66:67]
	v_add_co_u32_e32 v66, vcc, 0x5000, v186
	v_lshl_add_u64 v[100:101], v[60:61], 0, v[150:151]
	s_nop 0
	v_addc_co_u32_e32 v67, vcc, 0, v187, vcc
	v_add_co_u32_e32 v70, vcc, 0x8000, v186
	global_store_dwordx2 v[100:101], v[58:59], off
	s_nop 0
	v_addc_co_u32_e32 v71, vcc, 0, v187, vcc
	v_add_co_u32_e32 v74, vcc, 0xb000, v186
	global_load_dwordx4 v[58:61], v[186:187], off offset:16
	s_nop 0
	v_addc_co_u32_e32 v75, vcc, 0, v187, vcc
	v_add_co_u32_e32 v78, vcc, 0xd000, v186
	global_load_dwordx4 v[62:65], v[62:63], off offset:3088
	s_nop 0
	global_load_dwordx4 v[66:69], v[66:67], off offset:2064
	v_addc_co_u32_e32 v79, vcc, 0, v187, vcc
	v_add_co_u32_e32 v86, vcc, 0x2000, v188
	global_load_dwordx4 v[70:73], v[70:71], off offset:1040
	s_nop 0
	global_load_dwordx4 v[74:77], v[74:75], off offset:16
	v_addc_co_u32_e32 v87, vcc, 0, v189, vcc
	global_load_dwordx4 v[78:81], v[78:79], off offset:3088
	s_nop 0
	global_load_dwordx4 v[82:85], v[188:189], off offset:16
	v_mov_b32_e32 v99, 0
	global_load_dwordx4 v[86:89], v[86:87], off offset:3088
	v_mov_b32_e32 v92, 0
	v_mov_b32_e32 v93, 0
	v_mov_b32_e32 v94, 0
	v_mov_b32_e32 v95, 0
	s_and_saveexec_b64 s[4:5], s[22:23]
	s_cbranch_execz .LBB0_1446
	ds_read_b128 v[96:99], v237
	ds_read_b128 v[92:95], v236
; #define LAS __attribute__((address_space(3)))
; __device__ __forceinline__ float silu_f(float x) { return x * __builtin_amdgcn_rcpf(1.f + __expf(-x)); }
;     __device__ __forceinline__ void operator()(const f32x4 (&acc_c)[2][2][4][2], const Unit& u, int wr, int wc, int fr, int fq) const {
;     ...
;             for (int ai = 0; ai < 2; ++ai) {
;                 f32x4 xpg = {0.f, 0.f, 0.f, 0.f}, xpv = {0.f, 0.f, 0.f, 0.f};
;                 const bool top = (ai == 0 && wr == 0);
;                 if (!top && fr >= 14) { const int ps = (wr == 1) ? ((ai * 2) * 4 + wc) : (((ai - 1) * 2 + 1) * 4 + wc);
;                     xpg = *(const LAS f32x4*)(xch + ps * 128 + (fr - 14) * 64 + 8 * fq + 4 * n); xpv = *(const LAS f32x4*)(xch + ps * 128 + (fr - 14) * 64 + 32 + 8 * fq + 4 * n); }
; #pragma unroll
;                 for (int m = 0; m < 4; ++m) {
;                     const f32x4 cg = acc[ai][0][m][n], cv = acc[ai][1][m][n];
;                     const f32x4 pg = m ? acc[ai][0][m - 1][n] : xpg, pv = m ? acc[ai][1][m - 1][n] : xpv;
;                     h16x4 o;
; #pragma unroll
;                     for (int e = 0; e < 4; ++e) {
;                         const float g1 = dppmov<0x111>(dppmov<0x121>(0.f, pg[e]), cg[e]), g2 = dppmov<0x112>(dppmov<0x122>(0.f, pg[e]), cg[e]);
;                         const float v1 = dppmov<0x111>(dppmov<0x121>(0.f, pv[e]), cv[e]), v2 = dppmov<0x112>(dppmov<0x122>(0.f, pv[e]), cv[e]);
;                         const float gate = wg[0][e] * g2 + wg[1][e] * g1 + wg[2][e] * cg[e] + bg[e];
;                         const float val = wv[0][e] * v2 + wv[1][e] * v1 + wv[2][e] * cv[e] + bv[e];
;                         o[e] = (h16)(silu_f(gate) * val);
;                     }
;                     *(h16x4*)(act + (size_t)(row0 + ai * HALF + m * 16) * FF + ch0 + 4 * n) = o;
.LBB0_1446:
	s_or_b64 exec, exec, s[4:5]
	v_mov_b32_e32 v191, v190
	v_mov_b32_e32 v102, v190
	v_mov_b32_e32 v103, v190
	v_mov_b32_e32 v106, v128
	v_mov_b32_e32 v107, v128
	v_mov_b32_e32 v129, v128
	v_pk_mul_f32 v[48:49], v[48:49], v[102:103]
	v_pk_mul_f32 v[104:105], v[46:47], v[190:191]
	v_pk_mul_f32 v[46:47], v[40:41], v[102:103]
	v_pk_mul_f32 v[102:103], v[38:39], v[190:191]
	v_pk_mul_f32 v[38:39], v[44:45], v[106:107]
	v_pk_mul_f32 v[40:41], v[42:43], v[128:129]
	s_waitcnt lgkmcnt(1)
	v_mov_b32_dpp v44, v96 row_ror:2 row_mask:0xf bank_mask:0xf
	v_mov_b32_dpp v45, v97 row_ror:2 row_mask:0xf bank_mask:0xf
	v_mov_b32_dpp v42, v96 row_ror:1 row_mask:0xf bank_mask:0xf
	v_mov_b32_dpp v44, v182 row_shr:2 row_mask:0xf bank_mask:0xf
	v_mov_b32_dpp v43, v97 row_ror:1 row_mask:0xf bank_mask:0xf
	v_mov_b32_dpp v45, v183 row_shr:2 row_mask:0xf bank_mask:0xf
	v_mov_b32_dpp v42, v182 row_shr:1 row_mask:0xf bank_mask:0xf
	v_mov_b32_dpp v43, v183 row_shr:1 row_mask:0xf bank_mask:0xf
	s_waitcnt vmcnt(7)
	v_pk_mul_f32 v[44:45], v[58:59], v[44:45]
	v_pk_mul_f32 v[36:37], v[36:37], v[106:107]
	s_waitcnt vmcnt(5)
	v_pk_fma_f32 v[42:43], v[66:67], v[42:43], v[44:45]
	s_waitcnt vmcnt(3)
	v_pk_fma_f32 v[42:43], v[182:183], v[74:75], v[42:43]
	s_waitcnt vmcnt(1)
	v_pk_add_f32 v[42:43], v[82:83], v[42:43]
	v_mul_f32_e32 v0, 0xbfb8aa3b, v42
	v_exp_f32_e32 v0, v0
	v_mul_f32_e32 v44, 0xbfb8aa3b, v43
	v_exp_f32_e32 v45, v44
	s_waitcnt lgkmcnt(0)
	v_mov_b32_dpp v106, v92 row_ror:2 row_mask:0xf bank_mask:0xf
	v_add_f32_e32 v0, 1.0, v0
	v_mov_b32_dpp v107, v93 row_ror:2 row_mask:0xf bank_mask:0xf
	v_rcp_f32_e32 v44, v0
	v_add_f32_e32 v0, 1.0, v45
	v_mov_b32_dpp v96, v92 row_ror:1 row_mask:0xf bank_mask:0xf
	v_mov_b32_dpp v106, v184 row_shr:2 row_mask:0xf bank_mask:0xf
	v_mov_b32_dpp v97, v93 row_ror:1 row_mask:0xf bank_mask:0xf
	v_mov_b32_dpp v107, v185 row_shr:2 row_mask:0xf bank_mask:0xf
	v_rcp_f32_e32 v45, v0
	v_mov_b32_dpp v96, v184 row_shr:1 row_mask:0xf bank_mask:0xf
	v_mov_b32_dpp v97, v185 row_shr:1 row_mask:0xf bank_mask:0xf
	v_pk_mul_f32 v[92:93], v[62:63], v[106:107]
	v_pk_mul_f32 v[42:43], v[42:43], v[44:45]
	v_pk_fma_f32 v[92:93], v[70:71], v[96:97], v[92:93]
	v_pk_fma_f32 v[92:93], v[184:185], v[78:79], v[92:93]
	s_waitcnt vmcnt(0)
	v_pk_add_f32 v[92:93], v[86:87], v[92:93]
	v_mov_b32_dpp v44, v98 row_ror:1 row_mask:0xf bank_mask:0xf
	v_pk_mul_f32 v[42:43], v[92:93], v[42:43]
	v_mov_b32_dpp v45, v99 row_ror:1 row_mask:0xf bank_mask:0xf
	v_mov_b32_dpp v92, v98 row_ror:2 row_mask:0xf bank_mask:0xf
	v_mov_b32_dpp v93, v99 row_ror:2 row_mask:0xf bank_mask:0xf
	v_mov_b32_dpp v44, v178 row_shr:1 row_mask:0xf bank_mask:0xf
	v_mov_b32_dpp v92, v178 row_shr:2 row_mask:0xf bank_mask:0xf
	v_mov_b32_dpp v93, v179 row_shr:2 row_mask:0xf bank_mask:0xf
	v_mov_b32_dpp v45, v179 row_shr:1 row_mask:0xf bank_mask:0xf
	v_pk_mul_f32 v[92:93], v[60:61], v[92:93]
	v_cvt_pk_f16_f32 v42, v42, v43
	v_pk_fma_f32 v[44:45], v[68:69], v[44:45], v[92:93]
	v_pk_fma_f32 v[44:45], v[178:179], v[76:77], v[44:45]
	v_pk_add_f32 v[44:45], v[84:85], v[44:45]
	v_mul_f32_e32 v0, 0xbfb8aa3b, v44
	v_exp_f32_e32 v0, v0
	v_mul_f32_e32 v43, 0xbfb8aa3b, v45
	v_exp_f32_e32 v43, v43
	v_mov_b32_dpp v98, v94 row_ror:2 row_mask:0xf bank_mask:0xf
	v_add_f32_e32 v0, 1.0, v0
	v_mov_b32_dpp v99, v95 row_ror:2 row_mask:0xf bank_mask:0xf
	v_rcp_f32_e32 v92, v0
	v_add_f32_e32 v0, 1.0, v43
	v_mov_b32_dpp v96, v94 row_ror:1 row_mask:0xf bank_mask:0xf
	v_mov_b32_dpp v98, v180 row_shr:2 row_mask:0xf bank_mask:0xf
	v_mov_b32_dpp v97, v95 row_ror:1 row_mask:0xf bank_mask:0xf
	v_mov_b32_dpp v99, v181 row_shr:2 row_mask:0xf bank_mask:0xf
	v_rcp_f32_e32 v93, v0
	v_mov_b32_dpp v96, v180 row_shr:1 row_mask:0xf bank_mask:0xf
	v_mov_b32_dpp v97, v181 row_shr:1 row_mask:0xf bank_mask:0xf
	v_pk_mul_f32 v[94:95], v[64:65], v[98:99]
	v_pk_mul_f32 v[44:45], v[44:45], v[92:93]
	v_pk_fma_f32 v[94:95], v[72:73], v[96:97], v[94:95]
	v_pk_fma_f32 v[94:95], v[180:181], v[80:81], v[94:95]
	v_pk_add_f32 v[94:95], v[88:89], v[94:95]
	v_mov_b32_dpp v92, v184 row_ror:1 row_mask:0xf bank_mask:0xf
	v_pk_mul_f32 v[44:45], v[94:95], v[44:45]
	v_cvt_pk_f16_f32 v43, v44, v45
	global_store_dwordx2 v[130:131], v[42:43], off offset:8
	v_mov_b32_dpp v44, v182 row_ror:2 row_mask:0xf bank_mask:0xf
	v_mov_b32_dpp v45, v183 row_ror:2 row_mask:0xf bank_mask:0xf
	v_mov_b32_dpp v42, v182 row_ror:1 row_mask:0xf bank_mask:0xf
	v_mov_b32_dpp v44, v104 row_shr:2 row_mask:0xf bank_mask:0xf
	v_mov_b32_dpp v43, v183 row_ror:1 row_mask:0xf bank_mask:0xf
	v_mov_b32_dpp v45, v105 row_shr:2 row_mask:0xf bank_mask:0xf
	v_mov_b32_dpp v42, v104 row_shr:1 row_mask:0xf bank_mask:0xf
	v_mov_b32_dpp v43, v105 row_shr:1 row_mask:0xf bank_mask:0xf
	v_pk_mul_f32 v[44:45], v[58:59], v[44:45]
	v_pk_fma_f32 v[42:43], v[66:67], v[42:43], v[44:45]
	v_mov_b32_dpp v94, v184 row_ror:2 row_mask:0xf bank_mask:0xf
	v_pk_fma_f32 v[42:43], v[104:105], v[74:75], v[42:43]
	v_mov_b32_dpp v95, v185 row_ror:2 row_mask:0xf bank_mask:0xf
	v_pk_add_f32 v[42:43], v[82:83], v[42:43]
	v_mov_b32_dpp v94, v102 row_shr:2 row_mask:0xf bank_mask:0xf
	v_mul_f32_e32 v0, 0xbfb8aa3b, v42
	v_exp_f32_e32 v0, v0
	v_mul_f32_e32 v44, 0xbfb8aa3b, v43
	v_exp_f32_e32 v45, v44
	v_mov_b32_dpp v93, v185 row_ror:1 row_mask:0xf bank_mask:0xf
	v_add_f32_e32 v0, 1.0, v0
	v_rcp_f32_e32 v44, v0
	v_add_f32_e32 v0, 1.0, v45
	v_mov_b32_dpp v95, v103 row_shr:2 row_mask:0xf bank_mask:0xf
	v_rcp_f32_e32 v45, v0
	v_mov_b32_dpp v92, v102 row_shr:1 row_mask:0xf bank_mask:0xf
	v_mov_b32_dpp v93, v103 row_shr:1 row_mask:0xf bank_mask:0xf
	v_pk_mul_f32 v[94:95], v[62:63], v[94:95]
	v_pk_mul_f32 v[42:43], v[42:43], v[44:45]
; __device__ __forceinline__ float silu_f(float x) { return x * __builtin_amdgcn_rcpf(1.f + __expf(-x)); }
;     __device__ __forceinline__ void operator()(const f32x4 (&acc_c)[2][2][4][2], const Unit& u, int wr, int wc, int fr, int fq) const {
;     ...
;                 for (int m = 0; m < 4; ++m) {
;                     const f32x4 cg = acc[ai][0][m][n], cv = acc[ai][1][m][n];
;                     const f32x4 pg = m ? acc[ai][0][m - 1][n] : xpg, pv = m ? acc[ai][1][m - 1][n] : xpv;
;                     h16x4 o;
; #pragma unroll
;                     for (int e = 0; e < 4; ++e) {
;                         const float g1 = dppmov<0x111>(dppmov<0x121>(0.f, pg[e]), cg[e]), g2 = dppmov<0x112>(dppmov<0x122>(0.f, pg[e]), cg[e]);
;                         const float v1 = dppmov<0x111>(dppmov<0x121>(0.f, pv[e]), cv[e]), v2 = dppmov<0x112>(dppmov<0x122>(0.f, pv[e]), cv[e]);
;                         const float gate = wg[0][e] * g2 + wg[1][e] * g1 + wg[2][e] * cg[e] + bg[e];
;                         const float val = wv[0][e] * v2 + wv[1][e] * v1 + wv[2][e] * cv[e] + bv[e];
;                         o[e] = (h16)(silu_f(gate) * val);
;                     }
;                     *(h16x4*)(act + (size_t)(row0 + ai * HALF + m * 16) * FF + ch0 + 4 * n) = o;
	v_pk_fma_f32 v[92:93], v[70:71], v[92:93], v[94:95]
	v_pk_fma_f32 v[92:93], v[102:103], v[78:79], v[92:93]
	v_pk_add_f32 v[92:93], v[86:87], v[92:93]
	v_mov_b32_dpp v44, v178 row_ror:1 row_mask:0xf bank_mask:0xf
	v_pk_mul_f32 v[42:43], v[92:93], v[42:43]
	v_mov_b32_dpp v45, v179 row_ror:1 row_mask:0xf bank_mask:0xf
	v_mov_b32_dpp v92, v178 row_ror:2 row_mask:0xf bank_mask:0xf
	v_mov_b32_dpp v93, v179 row_ror:2 row_mask:0xf bank_mask:0xf
	v_mov_b32_dpp v44, v48 row_shr:1 row_mask:0xf bank_mask:0xf
	v_mov_b32_dpp v92, v48 row_shr:2 row_mask:0xf bank_mask:0xf
	v_mov_b32_dpp v93, v49 row_shr:2 row_mask:0xf bank_mask:0xf
	v_mov_b32_dpp v45, v49 row_shr:1 row_mask:0xf bank_mask:0xf
	v_pk_mul_f32 v[92:93], v[60:61], v[92:93]
	v_cvt_pk_f16_f32 v42, v42, v43
	v_pk_fma_f32 v[44:45], v[68:69], v[44:45], v[92:93]
	v_pk_fma_f32 v[44:45], v[48:49], v[76:77], v[44:45]
	v_pk_add_f32 v[44:45], v[84:85], v[44:45]
	v_mul_f32_e32 v0, 0xbfb8aa3b, v44
	v_exp_f32_e32 v0, v0
	v_mul_f32_e32 v43, 0xbfb8aa3b, v45
	v_exp_f32_e32 v43, v43
	v_mov_b32_dpp v96, v180 row_ror:2 row_mask:0xf bank_mask:0xf
	v_add_f32_e32 v0, 1.0, v0
	v_mov_b32_dpp v97, v181 row_ror:2 row_mask:0xf bank_mask:0xf
	v_rcp_f32_e32 v92, v0
	v_add_f32_e32 v0, 1.0, v43
	v_mov_b32_dpp v94, v180 row_ror:1 row_mask:0xf bank_mask:0xf
	v_mov_b32_dpp v96, v46 row_shr:2 row_mask:0xf bank_mask:0xf
	v_mov_b32_dpp v95, v181 row_ror:1 row_mask:0xf bank_mask:0xf
	v_mov_b32_dpp v97, v47 row_shr:2 row_mask:0xf bank_mask:0xf
	v_rcp_f32_e32 v93, v0
	v_mov_b32_dpp v94, v46 row_shr:1 row_mask:0xf bank_mask:0xf
	v_mov_b32_dpp v95, v47 row_shr:1 row_mask:0xf bank_mask:0xf
	v_pk_mul_f32 v[96:97], v[64:65], v[96:97]
	v_pk_mul_f32 v[44:45], v[44:45], v[92:93]
	v_pk_fma_f32 v[94:95], v[72:73], v[94:95], v[96:97]
	v_pk_mul_f32 v[34:35], v[34:35], v[128:129]
	v_pk_fma_f32 v[94:95], v[46:47], v[80:81], v[94:95]
	v_pk_add_f32 v[94:95], v[88:89], v[94:95]
	v_pk_mul_f32 v[44:45], v[94:95], v[44:45]
	v_cvt_pk_f16_f32 v43, v44, v45
	global_store_dwordx2 v[132:133], v[42:43], off offset:8
	v_mov_b32_dpp v44, v104 row_ror:2 row_mask:0xf bank_mask:0xf
	v_mov_b32_dpp v45, v105 row_ror:2 row_mask:0xf bank_mask:0xf
	v_mov_b32_dpp v42, v104 row_ror:1 row_mask:0xf bank_mask:0xf
	v_mov_b32_dpp v44, v40 row_shr:2 row_mask:0xf bank_mask:0xf
	v_mov_b32_dpp v43, v105 row_ror:1 row_mask:0xf bank_mask:0xf
	v_mov_b32_dpp v45, v41 row_shr:2 row_mask:0xf bank_mask:0xf
	v_mov_b32_dpp v42, v40 row_shr:1 row_mask:0xf bank_mask:0xf
	v_mov_b32_dpp v43, v41 row_shr:1 row_mask:0xf bank_mask:0xf
	v_pk_mul_f32 v[44:45], v[58:59], v[44:45]
	v_pk_fma_f32 v[42:43], v[66:67], v[42:43], v[44:45]
	v_mov_b32_dpp v94, v102 row_ror:2 row_mask:0xf bank_mask:0xf
	v_pk_fma_f32 v[42:43], v[40:41], v[74:75], v[42:43]
	v_mov_b32_dpp v95, v103 row_ror:2 row_mask:0xf bank_mask:0xf
	v_pk_add_f32 v[42:43], v[82:83], v[42:43]
	v_mov_b32_dpp v92, v102 row_ror:1 row_mask:0xf bank_mask:0xf
	v_mul_f32_e32 v0, 0xbfb8aa3b, v42
	v_exp_f32_e32 v0, v0
	v_mul_f32_e32 v44, 0xbfb8aa3b, v43
	v_exp_f32_e32 v45, v44
	v_mov_b32_dpp v94, v34 row_shr:2 row_mask:0xf bank_mask:0xf
	v_add_f32_e32 v0, 1.0, v0
	v_rcp_f32_e32 v44, v0
	v_add_f32_e32 v0, 1.0, v45
	v_mov_b32_dpp v93, v103 row_ror:1 row_mask:0xf bank_mask:0xf
	v_mov_b32_dpp v95, v35 row_shr:2 row_mask:0xf bank_mask:0xf
	v_rcp_f32_e32 v45, v0
	v_mov_b32_dpp v92, v34 row_shr:1 row_mask:0xf bank_mask:0xf
	v_mov_b32_dpp v93, v35 row_shr:1 row_mask:0xf bank_mask:0xf
	v_pk_mul_f32 v[94:95], v[62:63], v[94:95]
	v_pk_mul_f32 v[42:43], v[42:43], v[44:45]
	v_pk_fma_f32 v[92:93], v[70:71], v[92:93], v[94:95]
	v_pk_fma_f32 v[92:93], v[34:35], v[78:79], v[92:93]
	v_pk_add_f32 v[92:93], v[86:87], v[92:93]
	v_mov_b32_dpp v44, v48 row_ror:1 row_mask:0xf bank_mask:0xf
	v_pk_mul_f32 v[42:43], v[92:93], v[42:43]
	v_mov_b32_dpp v92, v48 row_ror:2 row_mask:0xf bank_mask:0xf
	v_mov_b32_dpp v93, v49 row_ror:2 row_mask:0xf bank_mask:0xf
	s_nop 0
	v_mov_b32_dpp v92, v38 row_shr:2 row_mask:0xf bank_mask:0xf
	v_mov_b32_dpp v45, v49 row_ror:1 row_mask:0xf bank_mask:0xf
	v_mov_b32_dpp v93, v39 row_shr:2 row_mask:0xf bank_mask:0xf
	v_mov_b32_dpp v44, v38 row_shr:1 row_mask:0xf bank_mask:0xf
	v_mov_b32_dpp v48, v46 row_ror:1 row_mask:0xf bank_mask:0xf
	v_mov_b32_dpp v94, v46 row_ror:2 row_mask:0xf bank_mask:0xf
	v_mov_b32_dpp v45, v39 row_shr:1 row_mask:0xf bank_mask:0xf
	v_mov_b32_dpp v49, v47 row_ror:1 row_mask:0xf bank_mask:0xf
	v_mov_b32_dpp v95, v47 row_ror:2 row_mask:0xf bank_mask:0xf
	v_pk_mul_f32 v[46:47], v[60:61], v[92:93]
	v_cvt_pk_f16_f32 v42, v42, v43
	v_pk_fma_f32 v[44:45], v[68:69], v[44:45], v[46:47]
	v_mov_b32_dpp v94, v36 row_shr:2 row_mask:0xf bank_mask:0xf
; __device__ __forceinline__ float silu_f(float x) { return x * __builtin_amdgcn_rcpf(1.f + __expf(-x)); }
;     __device__ __forceinline__ void operator()(const f32x4 (&acc_c)[2][2][4][2], const Unit& u, int wr, int wc, int fr, int fq) const {
;     ...
;                 for (int m = 0; m < 4; ++m) {
;                     const f32x4 cg = acc[ai][0][m][n], cv = acc[ai][1][m][n];
;                     const f32x4 pg = m ? acc[ai][0][m - 1][n] : xpg, pv = m ? acc[ai][1][m - 1][n] : xpv;
;                     h16x4 o;
; #pragma unroll
;                     for (int e = 0; e < 4; ++e) {
;                         const float g1 = dppmov<0x111>(dppmov<0x121>(0.f, pg[e]), cg[e]), g2 = dppmov<0x112>(dppmov<0x122>(0.f, pg[e]), cg[e]);
;                         const float v1 = dppmov<0x111>(dppmov<0x121>(0.f, pv[e]), cv[e]), v2 = dppmov<0x112>(dppmov<0x122>(0.f, pv[e]), cv[e]);
;                         const float gate = wg[0][e] * g2 + wg[1][e] * g1 + wg[2][e] * cg[e] + bg[e];
;                         const float val = wv[0][e] * v2 + wv[1][e] * v1 + wv[2][e] * cv[e] + bv[e];
;                         o[e] = (h16)(silu_f(gate) * val);
;                     }
;                     *(h16x4*)(act + (size_t)(row0 + ai * HALF + m * 16) * FF + ch0 + 4 * n) = o;
;                 }
	v_pk_fma_f32 v[44:45], v[38:39], v[76:77], v[44:45]
	v_mov_b32_dpp v95, v37 row_shr:2 row_mask:0xf bank_mask:0xf
	v_pk_add_f32 v[44:45], v[84:85], v[44:45]
	v_mov_b32_dpp v48, v36 row_shr:1 row_mask:0xf bank_mask:0xf
	v_mul_f32_e32 v0, 0xbfb8aa3b, v44
	v_exp_f32_e32 v0, v0
	v_mul_f32_e32 v43, 0xbfb8aa3b, v45
	v_exp_f32_e32 v43, v43
	v_mov_b32_dpp v49, v37 row_shr:1 row_mask:0xf bank_mask:0xf
	v_add_f32_e32 v0, 1.0, v0
	v_rcp_f32_e32 v46, v0
	v_add_f32_e32 v0, 1.0, v43
	v_rcp_f32_e32 v47, v0
	v_pk_mul_f32 v[92:93], v[64:65], v[94:95]
	v_mov_b32_e32 v91, 0
	v_pk_fma_f32 v[48:49], v[72:73], v[48:49], v[92:93]
	v_pk_mul_f32 v[44:45], v[44:45], v[46:47]
	v_pk_fma_f32 v[48:49], v[36:37], v[80:81], v[48:49]
	v_pk_add_f32 v[48:49], v[88:89], v[48:49]
	v_pk_mul_f32 v[44:45], v[48:49], v[44:45]
	v_mov_b32_dpp v46, v34 row_ror:2 row_mask:0xf bank_mask:0xf
	v_cvt_pk_f16_f32 v43, v44, v45
	global_store_dwordx2 v[134:135], v[42:43], off offset:8
	v_mov_b32_dpp v44, v40 row_ror:2 row_mask:0xf bank_mask:0xf
	v_mov_b32_dpp v45, v41 row_ror:2 row_mask:0xf bank_mask:0xf
	v_mov_b32_dpp v42, v40 row_ror:1 row_mask:0xf bank_mask:0xf
	v_mov_b32_dpp v44, v54 row_shr:2 row_mask:0xf bank_mask:0xf
	v_mov_b32_dpp v43, v41 row_ror:1 row_mask:0xf bank_mask:0xf
	v_mov_b32_dpp v45, v55 row_shr:2 row_mask:0xf bank_mask:0xf
	v_mov_b32_dpp v42, v54 row_shr:1 row_mask:0xf bank_mask:0xf
	v_mov_b32_dpp v40, v34 row_ror:1 row_mask:0xf bank_mask:0xf
	v_mov_b32_dpp v43, v55 row_shr:1 row_mask:0xf bank_mask:0xf
	v_mov_b32_dpp v41, v35 row_ror:1 row_mask:0xf bank_mask:0xf
	v_mov_b32_dpp v47, v35 row_ror:2 row_mask:0xf bank_mask:0xf
	v_pk_mul_f32 v[34:35], v[58:59], v[44:45]
	v_mov_b32_dpp v46, v50 row_shr:2 row_mask:0xf bank_mask:0xf
	v_pk_fma_f32 v[34:35], v[66:67], v[42:43], v[34:35]
	v_mov_b32_dpp v47, v51 row_shr:2 row_mask:0xf bank_mask:0xf
	v_pk_fma_f32 v[34:35], v[54:55], v[74:75], v[34:35]
	v_mov_b32_dpp v40, v50 row_shr:1 row_mask:0xf bank_mask:0xf
	v_pk_add_f32 v[34:35], v[82:83], v[34:35]
	v_mov_b32_dpp v41, v51 row_shr:1 row_mask:0xf bank_mask:0xf
	v_mul_f32_e32 v0, 0xbfb8aa3b, v34
	v_exp_f32_e32 v0, v0
	v_mul_f32_e32 v42, 0xbfb8aa3b, v35
	v_exp_f32_e32 v43, v42
	v_pk_mul_f32 v[44:45], v[62:63], v[46:47]
	v_add_f32_e32 v0, 1.0, v0
	v_rcp_f32_e32 v42, v0
	v_add_f32_e32 v0, 1.0, v43
	v_rcp_f32_e32 v43, v0
	v_pk_fma_f32 v[40:41], v[70:71], v[40:41], v[44:45]
	v_pk_fma_f32 v[40:41], v[50:51], v[78:79], v[40:41]
	v_pk_mul_f32 v[34:35], v[34:35], v[42:43]
	v_pk_add_f32 v[40:41], v[86:87], v[40:41]
	v_pk_mul_f32 v[34:35], v[40:41], v[34:35]
	v_mov_b32_dpp v42, v38 row_ror:2 row_mask:0xf bank_mask:0xf
	v_mov_b32_dpp v43, v39 row_ror:2 row_mask:0xf bank_mask:0xf
	v_mov_b32_dpp v40, v38 row_ror:1 row_mask:0xf bank_mask:0xf
	v_mov_b32_dpp v42, v56 row_shr:2 row_mask:0xf bank_mask:0xf
	v_mov_b32_dpp v41, v39 row_ror:1 row_mask:0xf bank_mask:0xf
	v_mov_b32_dpp v43, v57 row_shr:2 row_mask:0xf bank_mask:0xf
	v_mov_b32_dpp v40, v56 row_shr:1 row_mask:0xf bank_mask:0xf
	v_mov_b32_dpp v38, v36 row_ror:1 row_mask:0xf bank_mask:0xf
	v_mov_b32_dpp v44, v36 row_ror:2 row_mask:0xf bank_mask:0xf
	v_mov_b32_dpp v41, v57 row_shr:1 row_mask:0xf bank_mask:0xf
	v_mov_b32_dpp v39, v37 row_ror:1 row_mask:0xf bank_mask:0xf
	v_mov_b32_dpp v45, v37 row_ror:2 row_mask:0xf bank_mask:0xf
	v_pk_mul_f32 v[36:37], v[60:61], v[42:43]
	v_cvt_pk_f16_f32 v34, v34, v35
	v_pk_fma_f32 v[36:37], v[68:69], v[40:41], v[36:37]
	v_mov_b32_dpp v44, v52 row_shr:2 row_mask:0xf bank_mask:0xf
	v_pk_fma_f32 v[36:37], v[56:57], v[76:77], v[36:37]
	v_mov_b32_dpp v45, v53 row_shr:2 row_mask:0xf bank_mask:0xf
	v_pk_add_f32 v[36:37], v[84:85], v[36:37]
	v_mov_b32_dpp v38, v52 row_shr:1 row_mask:0xf bank_mask:0xf
	v_mul_f32_e32 v0, 0xbfb8aa3b, v36
	v_exp_f32_e32 v0, v0
	v_mul_f32_e32 v35, 0xbfb8aa3b, v37
	v_exp_f32_e32 v35, v35
	v_mov_b32_dpp v39, v53 row_shr:1 row_mask:0xf bank_mask:0xf
	v_add_f32_e32 v0, 1.0, v0
	v_rcp_f32_e32 v40, v0
	v_add_f32_e32 v0, 1.0, v35
	v_rcp_f32_e32 v41, v0
	v_pk_mul_f32 v[42:43], v[64:65], v[44:45]
	v_mov_b32_e32 v92, 0
	v_pk_fma_f32 v[38:39], v[72:73], v[38:39], v[42:43]
	v_pk_mul_f32 v[36:37], v[36:37], v[40:41]
	v_pk_fma_f32 v[38:39], v[52:53], v[80:81], v[38:39]
	v_mov_b32_e32 v93, 0
	v_pk_add_f32 v[38:39], v[88:89], v[38:39]
	s_nop 0
	v_pk_mul_f32 v[36:37], v[38:39], v[36:37]
	s_nop 0
	v_cvt_pk_f16_f32 v35, v36, v37
	global_store_dwordx2 v[136:137], v[34:35], off offset:8
	v_mov_b32_e32 v34, 0
	v_mov_b32_e32 v35, 0
	v_mov_b32_e32 v36, 0
	v_mov_b32_e32 v37, 0
	s_and_saveexec_b64 s[4:5], s[6:7]
	s_cbranch_execz .LBB0_1431
	ds_read_b128 v[90:93], v239
	ds_read_b128 v[34:37], v238
	s_branch .LBB0_1431
